# merged-wait version with the trailing half taking its offset barrier right after its epilogue (barrier-first unit boundary)
# speedup vs baseline: 1.0067x; 1.0017x over previous
.Lpeel_p1:
	s_waitcnt lgkmcnt(0)
	s_add_i32 s7, s4, 0xfff84000
	s_cmp_eq_u32 s6, 28
	s_cselect_b32 s17, s0, s7
	s_cselect_b32 s16, s1, s5
	s_or_b32 s7, s17, 0x4000
	s_mov_b32 m0, s79
	s_nop 0
	buffer_load_dwordx4 v242, s[24:27], s4 offen lds
	s_nop 0
	s_mov_b32 m0, s83
	s_nop 0
	buffer_load_dwordx4 v243, s[24:27], s4 offen lds
	s_waitcnt vmcnt(24) lgkmcnt(0)
	s_barrier
	s_waitcnt lgkmcnt(7)
	v_mfma_f32_16x16x32_bf16 v[180:183], v[16:19], v[192:195], 0
	v_mfma_f32_16x16x32_bf16 v[164:167], v[24:27], v[192:195], 0
	s_waitcnt lgkmcnt(5)
	v_mfma_f32_16x16x32_bf16 v[148:151], v[16:19], v[200:203], 0
	v_mfma_f32_16x16x32_bf16 v[140:143], v[24:27], v[200:203], 0
	s_waitcnt lgkmcnt(3)
	v_mfma_f32_16x16x32_bf16 v[132:135], v[16:19], v[220:223], 0
	v_mfma_f32_16x16x32_bf16 v[124:127], v[24:27], v[220:223], 0
	s_waitcnt lgkmcnt(1)
	v_mfma_f32_16x16x32_bf16 v[116:119], v[16:19], v[228:231], 0
	v_mfma_f32_16x16x32_bf16 v[108:111], v[24:27], v[228:231], 0
	v_mfma_f32_16x16x32_bf16 v[180:183], v[20:23], v[196:199], v[180:183]
	v_mfma_f32_16x16x32_bf16 v[164:167], v[28:31], v[196:199], v[164:167]
	v_mfma_f32_16x16x32_bf16 v[148:151], v[20:23], v[204:207], v[148:151]
	v_mfma_f32_16x16x32_bf16 v[140:143], v[28:31], v[204:207], v[140:143]
	v_mfma_f32_16x16x32_bf16 v[132:135], v[20:23], v[224:227], v[132:135]
	v_mfma_f32_16x16x32_bf16 v[124:127], v[28:31], v[224:227], v[124:127]
	s_waitcnt lgkmcnt(0)
	v_mfma_f32_16x16x32_bf16 v[116:119], v[20:23], v[246:249], v[116:119]
	v_mfma_f32_16x16x32_bf16 v[108:111], v[28:31], v[246:249], v[108:111]
	v_mfma_f32_16x16x32_bf16 v[172:175], v[152:155], v[192:195], 0
	v_mfma_f32_16x16x32_bf16 v[156:159], v[168:171], v[192:195], 0
	v_mfma_f32_16x16x32_bf16 v[144:147], v[152:155], v[200:203], 0
	v_mfma_f32_16x16x32_bf16 v[136:139], v[168:171], v[200:203], 0
	v_mfma_f32_16x16x32_bf16 v[128:131], v[152:155], v[220:223], 0
	v_mfma_f32_16x16x32_bf16 v[120:123], v[168:171], v[220:223], 0
	v_mfma_f32_16x16x32_bf16 v[112:115], v[152:155], v[228:231], 0
	v_mfma_f32_16x16x32_bf16 v[104:107], v[168:171], v[228:231], 0
	v_mfma_f32_16x16x32_bf16 v[172:175], v[160:163], v[196:199], v[172:175]
	v_mfma_f32_16x16x32_bf16 v[156:159], v[176:179], v[196:199], v[156:159]
	v_mfma_f32_16x16x32_bf16 v[144:147], v[160:163], v[204:207], v[144:147]
	v_mfma_f32_16x16x32_bf16 v[136:139], v[176:179], v[204:207], v[136:139]
	v_mfma_f32_16x16x32_bf16 v[128:131], v[160:163], v[224:227], v[128:131]
	v_mfma_f32_16x16x32_bf16 v[120:123], v[176:179], v[224:227], v[120:123]
	v_mfma_f32_16x16x32_bf16 v[112:115], v[160:163], v[246:249], v[112:115]
	v_mfma_f32_16x16x32_bf16 v[104:107], v[176:179], v[246:249], v[104:107]
	s_barrier
	ds_read_b128 v[192:195], v245 offset:16384
	ds_read_b128 v[196:199], v245 offset:17408
	ds_read_b128 v[200:203], v245 offset:18432
	ds_read_b128 v[204:207], v245 offset:19456
	ds_read_b128 v[220:223], v245 offset:20480
	ds_read_b128 v[224:227], v245 offset:21504
	ds_read_b128 v[228:231], v245 offset:22528
	ds_read_b128 v[246:249], v245 offset:23552
	s_mov_b32 m0, s51
	s_nop 0
	buffer_load_dwordx4 v242, s[56:59], s16 offen lds
	s_add_i32 s18, s16, 0x80000
	s_mov_b32 m0, s52
	s_nop 0
	buffer_load_dwordx4 v243, s[56:59], s16 offen lds
	s_nop 0
	s_mov_b32 m0, s53
	s_nop 0
	buffer_load_dwordx4 v242, s[56:59], s18 offen lds
	s_nop 0
	s_mov_b32 m0, s55
	s_nop 0
	buffer_load_dwordx4 v243, s[56:59], s18 offen lds
	s_nop 0
	s_mov_b32 m0, s31
	s_nop 0
	buffer_load_dwordx4 v242, s[24:27], s17 offen lds
	s_nop 0
	s_mov_b32 m0, s68
	s_nop 0
	buffer_load_dwordx4 v243, s[24:27], s17 offen lds
	s_waitcnt vmcnt(24) lgkmcnt(0)
	s_barrier
	s_waitcnt lgkmcnt(7)
	v_mfma_f32_16x16x32_bf16 v[76:79], v[16:19], v[192:195], 0
	v_mfma_f32_16x16x32_bf16 v[68:71], v[24:27], v[192:195], 0
	s_waitcnt lgkmcnt(5)
	v_mfma_f32_16x16x32_bf16 v[60:63], v[16:19], v[200:203], 0
	v_mfma_f32_16x16x32_bf16 v[52:55], v[24:27], v[200:203], 0
	s_waitcnt lgkmcnt(3)
	v_mfma_f32_16x16x32_bf16 v[44:47], v[16:19], v[220:223], 0
	v_mfma_f32_16x16x32_bf16 v[36:39], v[24:27], v[220:223], 0
	s_waitcnt lgkmcnt(1)
	v_mfma_f32_16x16x32_bf16 v[12:15], v[16:19], v[228:231], 0
	v_mfma_f32_16x16x32_bf16 v[4:7], v[24:27], v[228:231], 0
	v_mfma_f32_16x16x32_bf16 v[76:79], v[20:23], v[196:199], v[76:79]
	v_mfma_f32_16x16x32_bf16 v[68:71], v[28:31], v[196:199], v[68:71]
	v_mfma_f32_16x16x32_bf16 v[60:63], v[20:23], v[204:207], v[60:63]
	v_mfma_f32_16x16x32_bf16 v[52:55], v[28:31], v[204:207], v[52:55]
	v_mfma_f32_16x16x32_bf16 v[44:47], v[20:23], v[224:227], v[44:47]
	v_mfma_f32_16x16x32_bf16 v[36:39], v[28:31], v[224:227], v[36:39]
	s_waitcnt lgkmcnt(0)
	v_mfma_f32_16x16x32_bf16 v[12:15], v[20:23], v[246:249], v[12:15]
	v_mfma_f32_16x16x32_bf16 v[4:7], v[28:31], v[246:249], v[4:7]
	v_mfma_f32_16x16x32_bf16 v[40:43], v[152:155], v[220:223], 0
	v_mfma_f32_16x16x32_bf16 v[32:35], v[168:171], v[220:223], 0
	v_mfma_f32_16x16x32_bf16 v[8:11], v[152:155], v[228:231], 0
	v_mfma_f32_16x16x32_bf16 v[0:3], v[168:171], v[228:231], 0
	v_mfma_f32_16x16x32_bf16 v[16:19], v[152:155], v[192:195], 0
	v_mfma_f32_16x16x32_bf16 v[20:23], v[168:171], v[192:195], 0
	v_mfma_f32_16x16x32_bf16 v[24:27], v[152:155], v[200:203], 0
	v_mfma_f32_16x16x32_bf16 v[28:31], v[168:171], v[200:203], 0
	v_mfma_f32_16x16x32_bf16 v[40:43], v[160:163], v[224:227], v[40:43]
	v_mfma_f32_16x16x32_bf16 v[32:35], v[176:179], v[224:227], v[32:35]
	v_mfma_f32_16x16x32_bf16 v[8:11], v[160:163], v[246:249], v[8:11]
	v_mfma_f32_16x16x32_bf16 v[0:3], v[176:179], v[246:249], v[0:3]
	v_mfma_f32_16x16x32_bf16 v[16:19], v[160:163], v[196:199], v[16:19]
	v_mfma_f32_16x16x32_bf16 v[20:23], v[176:179], v[196:199], v[20:23]
	v_mfma_f32_16x16x32_bf16 v[24:27], v[160:163], v[204:207], v[24:27]
	v_mfma_f32_16x16x32_bf16 v[28:31], v[176:179], v[204:207], v[28:31]
	s_barrier
	v_add_u32_e32 v72, 0x18000, v83
	v_add_u32_e32 v80, 0x1c000, v83
	ds_read_b128 v[48:51], v72
	ds_read_b128 v[56:59], v72 offset:1024
	ds_read_b128 v[64:67], v72 offset:2048
	ds_read_b128 v[72:75], v72 offset:3072
	ds_read_b128 v[152:155], v80
	ds_read_b128 v[160:163], v80 offset:1024
	ds_read_b128 v[168:171], v80 offset:2048
	ds_read_b128 v[176:179], v80 offset:3072
	ds_read_b128 v[192:195], v245 offset:32768
	ds_read_b128 v[196:199], v245 offset:33792
	ds_read_b128 v[200:203], v245 offset:34816
	ds_read_b128 v[204:207], v245 offset:35840
	ds_read_b128 v[220:223], v245 offset:36864
	ds_read_b128 v[224:227], v245 offset:37888
	ds_read_b128 v[228:231], v245 offset:38912
	ds_read_b128 v[246:249], v245 offset:39936
	s_add_i32 s17, s17, 0x80000
	s_mov_b32 m0, s69
	s_nop 0
	buffer_load_dwordx4 v242, s[24:27], s17 offen lds
	s_nop 0
	s_mov_b32 m0, s70
	s_nop 0
	buffer_load_dwordx4 v243, s[24:27], s17 offen lds
	s_waitcnt vmcnt(8) lgkmcnt(0)
	s_barrier
	s_waitcnt lgkmcnt(7)
	v_mfma_f32_16x16x32_bf16 v[180:183], v[48:51], v[192:195], v[180:183]
	v_mfma_f32_16x16x32_bf16 v[164:167], v[64:67], v[192:195], v[164:167]
	s_waitcnt lgkmcnt(5)
	v_mfma_f32_16x16x32_bf16 v[148:151], v[48:51], v[200:203], v[148:151]
	v_mfma_f32_16x16x32_bf16 v[140:143], v[64:67], v[200:203], v[140:143]
	s_waitcnt lgkmcnt(3)
	v_mfma_f32_16x16x32_bf16 v[132:135], v[48:51], v[220:223], v[132:135]
	v_mfma_f32_16x16x32_bf16 v[124:127], v[64:67], v[220:223], v[124:127]
	s_waitcnt lgkmcnt(1)
	v_mfma_f32_16x16x32_bf16 v[116:119], v[48:51], v[228:231], v[116:119]
	v_mfma_f32_16x16x32_bf16 v[108:111], v[64:67], v[228:231], v[108:111]
	v_mfma_f32_16x16x32_bf16 v[180:183], v[56:59], v[196:199], v[180:183]
	v_mfma_f32_16x16x32_bf16 v[164:167], v[72:75], v[196:199], v[164:167]
	v_mfma_f32_16x16x32_bf16 v[148:151], v[56:59], v[204:207], v[148:151]
	v_mfma_f32_16x16x32_bf16 v[140:143], v[72:75], v[204:207], v[140:143]
	v_mfma_f32_16x16x32_bf16 v[132:135], v[56:59], v[224:227], v[132:135]
	v_mfma_f32_16x16x32_bf16 v[124:127], v[72:75], v[224:227], v[124:127]
	s_waitcnt lgkmcnt(0)
	v_mfma_f32_16x16x32_bf16 v[116:119], v[56:59], v[246:249], v[116:119]
	v_mfma_f32_16x16x32_bf16 v[108:111], v[72:75], v[246:249], v[108:111]
	v_mfma_f32_16x16x32_bf16 v[172:175], v[152:155], v[192:195], v[172:175]
	v_mfma_f32_16x16x32_bf16 v[156:159], v[168:171], v[192:195], v[156:159]
	v_mfma_f32_16x16x32_bf16 v[144:147], v[152:155], v[200:203], v[144:147]
	v_mfma_f32_16x16x32_bf16 v[136:139], v[168:171], v[200:203], v[136:139]
	v_mfma_f32_16x16x32_bf16 v[128:131], v[152:155], v[220:223], v[128:131]
	v_mfma_f32_16x16x32_bf16 v[120:123], v[168:171], v[220:223], v[120:123]
	v_mfma_f32_16x16x32_bf16 v[112:115], v[152:155], v[228:231], v[112:115]
	v_mfma_f32_16x16x32_bf16 v[104:107], v[168:171], v[228:231], v[104:107]
	v_mfma_f32_16x16x32_bf16 v[172:175], v[160:163], v[196:199], v[172:175]
	v_mfma_f32_16x16x32_bf16 v[156:159], v[176:179], v[196:199], v[156:159]
	v_mfma_f32_16x16x32_bf16 v[144:147], v[160:163], v[204:207], v[144:147]
	v_mfma_f32_16x16x32_bf16 v[136:139], v[176:179], v[204:207], v[136:139]
	v_mfma_f32_16x16x32_bf16 v[128:131], v[160:163], v[224:227], v[128:131]
	v_mfma_f32_16x16x32_bf16 v[120:123], v[176:179], v[224:227], v[120:123]
	v_mfma_f32_16x16x32_bf16 v[112:115], v[160:163], v[246:249], v[112:115]
	v_mfma_f32_16x16x32_bf16 v[104:107], v[176:179], v[246:249], v[104:107]
	s_barrier
	ds_read_b128 v[192:195], v245 offset:49152
	ds_read_b128 v[196:199], v245 offset:50176
	ds_read_b128 v[200:203], v245 offset:51200
	ds_read_b128 v[204:207], v245 offset:52224
	ds_read_b128 v[220:223], v245 offset:53248
	ds_read_b128 v[224:227], v245 offset:54272
	ds_read_b128 v[228:231], v245 offset:55296
	ds_read_b128 v[246:249], v245 offset:56320
	s_or_b32 s17, s16, 0x4000
	s_mov_b32 m0, s73
	s_nop 0
	buffer_load_dwordx4 v242, s[56:59], s17 offen lds
	s_add_i32 s16, s16, 0x84000
	s_mov_b32 m0, s74
	s_nop 0
	buffer_load_dwordx4 v243, s[56:59], s17 offen lds
	s_nop 0
	s_mov_b32 m0, s77
	s_nop 0
	buffer_load_dwordx4 v242, s[56:59], s16 offen lds
	s_nop 0
	s_mov_b32 m0, s78
	s_nop 0
	buffer_load_dwordx4 v243, s[56:59], s16 offen lds
	s_nop 0
	s_mov_b32 m0, s75
	s_nop 0
	buffer_load_dwordx4 v242, s[24:27], s7 offen lds
	s_nop 0
	s_mov_b32 m0, s76
	s_nop 0
	buffer_load_dwordx4 v243, s[24:27], s7 offen lds
	s_waitcnt vmcnt(8) lgkmcnt(0)
	s_barrier
	s_waitcnt lgkmcnt(7)
	v_mfma_f32_16x16x32_bf16 v[76:79], v[48:51], v[192:195], v[76:79]
	v_mfma_f32_16x16x32_bf16 v[68:71], v[64:67], v[192:195], v[68:71]
	s_waitcnt lgkmcnt(5)
	v_mfma_f32_16x16x32_bf16 v[60:63], v[48:51], v[200:203], v[60:63]
	v_mfma_f32_16x16x32_bf16 v[52:55], v[64:67], v[200:203], v[52:55]
	s_waitcnt lgkmcnt(3)
	v_mfma_f32_16x16x32_bf16 v[44:47], v[48:51], v[220:223], v[44:47]
	v_mfma_f32_16x16x32_bf16 v[36:39], v[64:67], v[220:223], v[36:39]
	s_waitcnt lgkmcnt(1)
	v_mfma_f32_16x16x32_bf16 v[12:15], v[48:51], v[228:231], v[12:15]
	v_mfma_f32_16x16x32_bf16 v[4:7], v[64:67], v[228:231], v[4:7]
	v_mfma_f32_16x16x32_bf16 v[76:79], v[56:59], v[196:199], v[76:79]
	v_mfma_f32_16x16x32_bf16 v[68:71], v[72:75], v[196:199], v[68:71]
	v_mfma_f32_16x16x32_bf16 v[60:63], v[56:59], v[204:207], v[60:63]
	v_mfma_f32_16x16x32_bf16 v[52:55], v[72:75], v[204:207], v[52:55]
	v_mfma_f32_16x16x32_bf16 v[44:47], v[56:59], v[224:227], v[44:47]
	v_mfma_f32_16x16x32_bf16 v[36:39], v[72:75], v[224:227], v[36:39]
	s_waitcnt lgkmcnt(0)
	v_mfma_f32_16x16x32_bf16 v[12:15], v[56:59], v[246:249], v[12:15]
	v_mfma_f32_16x16x32_bf16 v[4:7], v[72:75], v[246:249], v[4:7]
	v_mfma_f32_16x16x32_bf16 v[16:19], v[152:155], v[192:195], v[16:19]
	v_mfma_f32_16x16x32_bf16 v[72:75], v[160:163], v[196:199], v[16:19]
	v_mfma_f32_16x16x32_bf16 v[16:19], v[168:171], v[192:195], v[20:23]
	v_mfma_f32_16x16x32_bf16 v[64:67], v[176:179], v[196:199], v[16:19]
	v_mfma_f32_16x16x32_bf16 v[16:19], v[152:155], v[200:203], v[24:27]
	v_mfma_f32_16x16x32_bf16 v[56:59], v[160:163], v[204:207], v[16:19]
	v_mfma_f32_16x16x32_bf16 v[16:19], v[168:171], v[200:203], v[28:31]
	v_mfma_f32_16x16x32_bf16 v[48:51], v[176:179], v[204:207], v[16:19]
	v_mfma_f32_16x16x32_bf16 v[16:19], v[152:155], v[220:223], v[40:43]
	v_mfma_f32_16x16x32_bf16 v[40:43], v[160:163], v[224:227], v[16:19]
	v_mfma_f32_16x16x32_bf16 v[16:19], v[168:171], v[220:223], v[32:35]
	v_mfma_f32_16x16x32_bf16 v[8:11], v[152:155], v[228:231], v[8:11]
	v_mfma_f32_16x16x32_bf16 v[0:3], v[168:171], v[228:231], v[0:3]
	v_mfma_f32_16x16x32_bf16 v[32:35], v[176:179], v[224:227], v[16:19]
	v_mfma_f32_16x16x32_bf16 v[8:11], v[160:163], v[246:249], v[8:11]
	v_mfma_f32_16x16x32_bf16 v[0:3], v[176:179], v[246:249], v[0:3]
	s_barrier
	s_add_i32 s6, s6, 2
	s_add_i32 s4, s4, 0x8000
	s_add_i32 s5, s5, 0x8000

.Lpeel_p4:
	s_waitcnt lgkmcnt(0)
	s_add_i32 s11, s8, 0xfff84000
	s_cmp_eq_u32 s10, 28
	s_cselect_b32 s13, s6, s11
	s_cselect_b32 s12, s7, s9
	s_or_b32 s11, s13, 0x4000
	s_mov_b32 m0, s89
	s_nop 0
	buffer_load_dwordx4 v220, s[64:67], s8 offen lds
	s_nop 0
	s_mov_b32 m0, s91
	s_nop 0
	buffer_load_dwordx4 v221, s[64:67], s8 offen lds
	s_waitcnt vmcnt(24) lgkmcnt(0)
	s_barrier
	s_waitcnt lgkmcnt(7)
	v_mfma_f32_16x16x32_bf16 v[164:167], v[128:131], v[184:187], 0
	v_mfma_f32_16x16x32_bf16 v[160:163], v[152:155], v[184:187], 0
	s_waitcnt lgkmcnt(5)
	v_mfma_f32_16x16x32_bf16 v[136:139], v[128:131], v[192:195], 0
	v_mfma_f32_16x16x32_bf16 v[132:135], v[152:155], v[192:195], 0
	s_waitcnt lgkmcnt(3)
	v_mfma_f32_16x16x32_bf16 v[116:119], v[128:131], v[200:203], 0
	v_mfma_f32_16x16x32_bf16 v[112:115], v[152:155], v[200:203], 0
	s_waitcnt lgkmcnt(1)
	v_mfma_f32_16x16x32_bf16 v[76:79], v[128:131], v[224:227], 0
	v_mfma_f32_16x16x32_bf16 v[72:75], v[152:155], v[224:227], 0
	v_mfma_f32_16x16x32_bf16 v[164:167], v[140:143], v[188:191], v[164:167]
	v_mfma_f32_16x16x32_bf16 v[160:163], v[156:159], v[188:191], v[160:163]
	v_mfma_f32_16x16x32_bf16 v[136:139], v[140:143], v[196:199], v[136:139]
	v_mfma_f32_16x16x32_bf16 v[132:135], v[156:159], v[196:199], v[132:135]
	v_mfma_f32_16x16x32_bf16 v[116:119], v[140:143], v[204:207], v[116:119]
	v_mfma_f32_16x16x32_bf16 v[112:115], v[156:159], v[204:207], v[112:115]
	s_waitcnt lgkmcnt(0)
	v_mfma_f32_16x16x32_bf16 v[76:79], v[140:143], v[228:231], v[76:79]
	v_mfma_f32_16x16x32_bf16 v[72:75], v[156:159], v[228:231], v[72:75]
	v_mfma_f32_16x16x32_bf16 v[148:151], v[168:171], v[184:187], 0
	v_mfma_f32_16x16x32_bf16 v[144:147], v[176:179], v[184:187], 0
	v_mfma_f32_16x16x32_bf16 v[124:127], v[168:171], v[192:195], 0
	v_mfma_f32_16x16x32_bf16 v[120:123], v[176:179], v[192:195], 0
	v_mfma_f32_16x16x32_bf16 v[108:111], v[168:171], v[200:203], 0
	v_mfma_f32_16x16x32_bf16 v[104:107], v[176:179], v[200:203], 0
	v_mfma_f32_16x16x32_bf16 v[68:71], v[168:171], v[224:227], 0
	v_mfma_f32_16x16x32_bf16 v[64:67], v[176:179], v[224:227], 0
	v_mfma_f32_16x16x32_bf16 v[148:151], v[172:175], v[188:191], v[148:151]
	v_mfma_f32_16x16x32_bf16 v[144:147], v[180:183], v[188:191], v[144:147]
	v_mfma_f32_16x16x32_bf16 v[124:127], v[172:175], v[196:199], v[124:127]
	v_mfma_f32_16x16x32_bf16 v[120:123], v[180:183], v[196:199], v[120:123]
	v_mfma_f32_16x16x32_bf16 v[108:111], v[172:175], v[204:207], v[108:111]
	v_mfma_f32_16x16x32_bf16 v[104:107], v[180:183], v[204:207], v[104:107]
	v_mfma_f32_16x16x32_bf16 v[68:71], v[172:175], v[228:231], v[68:71]
	v_mfma_f32_16x16x32_bf16 v[64:67], v[180:183], v[228:231], v[64:67]
	s_barrier
	ds_read_b128 v[184:187], v223 offset:16384
	ds_read_b128 v[188:191], v223 offset:17408
	ds_read_b128 v[192:195], v223 offset:18432
	ds_read_b128 v[196:199], v223 offset:19456
	ds_read_b128 v[200:203], v223 offset:20480
	ds_read_b128 v[204:207], v223 offset:21504
	ds_read_b128 v[224:227], v223 offset:22528
	ds_read_b128 v[228:231], v223 offset:23552
	s_mov_b32 m0, s55
	s_nop 0
	buffer_load_dwordx4 v220, s[48:51], s12 offen lds
	s_add_i32 s14, s12, 0x80000
	s_mov_b32 m0, s76
	s_nop 0
	buffer_load_dwordx4 v221, s[48:51], s12 offen lds
	s_nop 0
	s_mov_b32 m0, s77
	s_nop 0
	buffer_load_dwordx4 v220, s[48:51], s14 offen lds
	s_nop 0
	s_mov_b32 m0, s78
	s_nop 0
	buffer_load_dwordx4 v221, s[48:51], s14 offen lds
	s_nop 0
	s_mov_b32 m0, s31
	s_nop 0
	buffer_load_dwordx4 v220, s[64:67], s13 offen lds
	s_nop 0
	s_mov_b32 m0, s79
	s_nop 0
	buffer_load_dwordx4 v221, s[64:67], s13 offen lds
	s_waitcnt vmcnt(24) lgkmcnt(0)
	s_barrier
	s_waitcnt lgkmcnt(7)
	v_mfma_f32_16x16x32_bf16 v[60:63], v[128:131], v[184:187], 0
	v_mfma_f32_16x16x32_bf16 v[56:59], v[152:155], v[184:187], 0
	s_waitcnt lgkmcnt(5)
	v_mfma_f32_16x16x32_bf16 v[44:47], v[128:131], v[192:195], 0
	v_mfma_f32_16x16x32_bf16 v[40:43], v[152:155], v[192:195], 0
	s_waitcnt lgkmcnt(3)
	v_mfma_f32_16x16x32_bf16 v[28:31], v[128:131], v[200:203], 0
	v_mfma_f32_16x16x32_bf16 v[24:27], v[152:155], v[200:203], 0
	s_waitcnt lgkmcnt(1)
	v_mfma_f32_16x16x32_bf16 v[12:15], v[128:131], v[224:227], 0
	v_mfma_f32_16x16x32_bf16 v[8:11], v[152:155], v[224:227], 0
	v_mfma_f32_16x16x32_bf16 v[60:63], v[140:143], v[188:191], v[60:63]
	v_mfma_f32_16x16x32_bf16 v[56:59], v[156:159], v[188:191], v[56:59]
	v_mfma_f32_16x16x32_bf16 v[44:47], v[140:143], v[196:199], v[44:47]
	v_mfma_f32_16x16x32_bf16 v[40:43], v[156:159], v[196:199], v[40:43]
	v_mfma_f32_16x16x32_bf16 v[28:31], v[140:143], v[204:207], v[28:31]
	v_mfma_f32_16x16x32_bf16 v[24:27], v[156:159], v[204:207], v[24:27]
	s_waitcnt lgkmcnt(0)
	v_mfma_f32_16x16x32_bf16 v[12:15], v[140:143], v[228:231], v[12:15]
	v_mfma_f32_16x16x32_bf16 v[8:11], v[156:159], v[228:231], v[8:11]
	v_mfma_f32_16x16x32_bf16 v[52:55], v[168:171], v[184:187], 0
	v_mfma_f32_16x16x32_bf16 v[48:51], v[176:179], v[184:187], 0
	v_mfma_f32_16x16x32_bf16 v[36:39], v[168:171], v[192:195], 0
	v_mfma_f32_16x16x32_bf16 v[32:35], v[176:179], v[192:195], 0
	v_mfma_f32_16x16x32_bf16 v[20:23], v[168:171], v[200:203], 0
	v_mfma_f32_16x16x32_bf16 v[16:19], v[176:179], v[200:203], 0
	v_mfma_f32_16x16x32_bf16 v[4:7], v[168:171], v[224:227], 0
	v_mfma_f32_16x16x32_bf16 v[0:3], v[176:179], v[224:227], 0
	v_mfma_f32_16x16x32_bf16 v[52:55], v[172:175], v[188:191], v[52:55]
	v_mfma_f32_16x16x32_bf16 v[48:51], v[180:183], v[188:191], v[48:51]
	v_mfma_f32_16x16x32_bf16 v[36:39], v[172:175], v[196:199], v[36:39]
	v_mfma_f32_16x16x32_bf16 v[32:35], v[180:183], v[196:199], v[32:35]
	v_mfma_f32_16x16x32_bf16 v[20:23], v[172:175], v[204:207], v[20:23]
	v_mfma_f32_16x16x32_bf16 v[16:19], v[180:183], v[204:207], v[16:19]
	v_mfma_f32_16x16x32_bf16 v[4:7], v[172:175], v[228:231], v[4:7]
	v_mfma_f32_16x16x32_bf16 v[0:3], v[180:183], v[228:231], v[0:3]
	s_barrier
	v_add_u32_e32 v156, 0x18000, v222
	v_add_u32_e32 v180, 0x1c000, v222
	ds_read_b128 v[128:131], v156
	ds_read_b128 v[140:143], v156 offset:1024
	ds_read_b128 v[152:155], v156 offset:2048
	ds_read_b128 v[156:159], v156 offset:3072
	ds_read_b128 v[168:171], v180
	ds_read_b128 v[172:175], v180 offset:1024
	ds_read_b128 v[176:179], v180 offset:2048
	ds_read_b128 v[180:183], v180 offset:3072
	ds_read_b128 v[184:187], v223 offset:32768
	ds_read_b128 v[188:191], v223 offset:33792
	ds_read_b128 v[192:195], v223 offset:34816
	ds_read_b128 v[196:199], v223 offset:35840
	ds_read_b128 v[200:203], v223 offset:36864
	ds_read_b128 v[204:207], v223 offset:37888
	ds_read_b128 v[224:227], v223 offset:38912
	ds_read_b128 v[228:231], v223 offset:39936
	s_add_i32 s13, s13, 0x80000
	s_mov_b32 m0, s82
	s_nop 0
	buffer_load_dwordx4 v220, s[64:67], s13 offen lds
	s_nop 0
	s_mov_b32 m0, s83
	s_nop 0
	buffer_load_dwordx4 v221, s[64:67], s13 offen lds
	s_waitcnt vmcnt(8) lgkmcnt(0)
	s_barrier
	s_waitcnt lgkmcnt(7)
	v_mfma_f32_16x16x32_bf16 v[164:167], v[128:131], v[184:187], v[164:167]
	v_mfma_f32_16x16x32_bf16 v[160:163], v[152:155], v[184:187], v[160:163]
	s_waitcnt lgkmcnt(5)
	v_mfma_f32_16x16x32_bf16 v[136:139], v[128:131], v[192:195], v[136:139]
	v_mfma_f32_16x16x32_bf16 v[132:135], v[152:155], v[192:195], v[132:135]
	s_waitcnt lgkmcnt(3)
	v_mfma_f32_16x16x32_bf16 v[116:119], v[128:131], v[200:203], v[116:119]
	v_mfma_f32_16x16x32_bf16 v[112:115], v[152:155], v[200:203], v[112:115]
	s_waitcnt lgkmcnt(1)
	v_mfma_f32_16x16x32_bf16 v[76:79], v[128:131], v[224:227], v[76:79]
	v_mfma_f32_16x16x32_bf16 v[72:75], v[152:155], v[224:227], v[72:75]
	v_mfma_f32_16x16x32_bf16 v[164:167], v[140:143], v[188:191], v[164:167]
	v_mfma_f32_16x16x32_bf16 v[160:163], v[156:159], v[188:191], v[160:163]
	v_mfma_f32_16x16x32_bf16 v[136:139], v[140:143], v[196:199], v[136:139]
	v_mfma_f32_16x16x32_bf16 v[132:135], v[156:159], v[196:199], v[132:135]
	v_mfma_f32_16x16x32_bf16 v[116:119], v[140:143], v[204:207], v[116:119]
	v_mfma_f32_16x16x32_bf16 v[112:115], v[156:159], v[204:207], v[112:115]
	s_waitcnt lgkmcnt(0)
	v_mfma_f32_16x16x32_bf16 v[76:79], v[140:143], v[228:231], v[76:79]
	v_mfma_f32_16x16x32_bf16 v[72:75], v[156:159], v[228:231], v[72:75]
	v_mfma_f32_16x16x32_bf16 v[148:151], v[168:171], v[184:187], v[148:151]
	v_mfma_f32_16x16x32_bf16 v[144:147], v[176:179], v[184:187], v[144:147]
	v_mfma_f32_16x16x32_bf16 v[124:127], v[168:171], v[192:195], v[124:127]
	v_mfma_f32_16x16x32_bf16 v[120:123], v[176:179], v[192:195], v[120:123]
	v_mfma_f32_16x16x32_bf16 v[108:111], v[168:171], v[200:203], v[108:111]
	v_mfma_f32_16x16x32_bf16 v[104:107], v[176:179], v[200:203], v[104:107]
	v_mfma_f32_16x16x32_bf16 v[68:71], v[168:171], v[224:227], v[68:71]
	v_mfma_f32_16x16x32_bf16 v[64:67], v[176:179], v[224:227], v[64:67]
	v_mfma_f32_16x16x32_bf16 v[148:151], v[172:175], v[188:191], v[148:151]
	v_mfma_f32_16x16x32_bf16 v[144:147], v[180:183], v[188:191], v[144:147]
	v_mfma_f32_16x16x32_bf16 v[124:127], v[172:175], v[196:199], v[124:127]
	v_mfma_f32_16x16x32_bf16 v[120:123], v[180:183], v[196:199], v[120:123]
	v_mfma_f32_16x16x32_bf16 v[108:111], v[172:175], v[204:207], v[108:111]
	v_mfma_f32_16x16x32_bf16 v[104:107], v[180:183], v[204:207], v[104:107]
	v_mfma_f32_16x16x32_bf16 v[68:71], v[172:175], v[228:231], v[68:71]
	v_mfma_f32_16x16x32_bf16 v[64:67], v[180:183], v[228:231], v[64:67]
	s_barrier
	ds_read_b128 v[184:187], v223 offset:49152
	ds_read_b128 v[188:191], v223 offset:50176
	ds_read_b128 v[192:195], v223 offset:51200
	ds_read_b128 v[196:199], v223 offset:52224
	ds_read_b128 v[200:203], v223 offset:53248
	ds_read_b128 v[204:207], v223 offset:54272
	ds_read_b128 v[224:227], v223 offset:55296
	ds_read_b128 v[228:231], v223 offset:56320
	s_or_b32 s13, s12, 0x4000
	s_mov_b32 m0, s34
	s_nop 0
	buffer_load_dwordx4 v220, s[48:51], s13 offen lds
	s_add_i32 s12, s12, 0x84000
	s_mov_b32 m0, s84
	s_nop 0
	buffer_load_dwordx4 v221, s[48:51], s13 offen lds
	s_nop 0
	s_mov_b32 m0, s87
	s_nop 0
	buffer_load_dwordx4 v220, s[48:51], s12 offen lds
	s_nop 0
	s_mov_b32 m0, s88
	s_nop 0
	buffer_load_dwordx4 v221, s[48:51], s12 offen lds
	s_nop 0
	s_mov_b32 m0, s85
	s_nop 0
	buffer_load_dwordx4 v220, s[64:67], s11 offen lds
	s_nop 0
	s_mov_b32 m0, s86
	s_nop 0
	buffer_load_dwordx4 v221, s[64:67], s11 offen lds
	s_waitcnt vmcnt(8) lgkmcnt(0)
	s_barrier
	s_waitcnt lgkmcnt(7)
	v_mfma_f32_16x16x32_bf16 v[60:63], v[128:131], v[184:187], v[60:63]
	v_mfma_f32_16x16x32_bf16 v[56:59], v[152:155], v[184:187], v[56:59]
	s_waitcnt lgkmcnt(5)
	v_mfma_f32_16x16x32_bf16 v[44:47], v[128:131], v[192:195], v[44:47]
	v_mfma_f32_16x16x32_bf16 v[40:43], v[152:155], v[192:195], v[40:43]
	s_waitcnt lgkmcnt(3)
	v_mfma_f32_16x16x32_bf16 v[28:31], v[128:131], v[200:203], v[28:31]
	v_mfma_f32_16x16x32_bf16 v[24:27], v[152:155], v[200:203], v[24:27]
	s_waitcnt lgkmcnt(1)
	v_mfma_f32_16x16x32_bf16 v[12:15], v[128:131], v[224:227], v[12:15]
	v_mfma_f32_16x16x32_bf16 v[8:11], v[152:155], v[224:227], v[8:11]
	v_mfma_f32_16x16x32_bf16 v[60:63], v[140:143], v[188:191], v[60:63]
	v_mfma_f32_16x16x32_bf16 v[56:59], v[156:159], v[188:191], v[56:59]
	v_mfma_f32_16x16x32_bf16 v[44:47], v[140:143], v[196:199], v[44:47]
	v_mfma_f32_16x16x32_bf16 v[40:43], v[156:159], v[196:199], v[40:43]
	v_mfma_f32_16x16x32_bf16 v[28:31], v[140:143], v[204:207], v[28:31]
	v_mfma_f32_16x16x32_bf16 v[24:27], v[156:159], v[204:207], v[24:27]
	s_waitcnt lgkmcnt(0)
	v_mfma_f32_16x16x32_bf16 v[12:15], v[140:143], v[228:231], v[12:15]
	v_mfma_f32_16x16x32_bf16 v[8:11], v[156:159], v[228:231], v[8:11]
	v_mfma_f32_16x16x32_bf16 v[52:55], v[168:171], v[184:187], v[52:55]
	v_mfma_f32_16x16x32_bf16 v[48:51], v[176:179], v[184:187], v[48:51]
	v_mfma_f32_16x16x32_bf16 v[36:39], v[168:171], v[192:195], v[36:39]
	v_mfma_f32_16x16x32_bf16 v[32:35], v[176:179], v[192:195], v[32:35]
	v_mfma_f32_16x16x32_bf16 v[20:23], v[168:171], v[200:203], v[20:23]
	v_mfma_f32_16x16x32_bf16 v[16:19], v[176:179], v[200:203], v[16:19]
	v_mfma_f32_16x16x32_bf16 v[4:7], v[168:171], v[224:227], v[4:7]
	v_mfma_f32_16x16x32_bf16 v[0:3], v[176:179], v[224:227], v[0:3]
	v_mfma_f32_16x16x32_bf16 v[52:55], v[172:175], v[188:191], v[52:55]
	v_mfma_f32_16x16x32_bf16 v[48:51], v[180:183], v[188:191], v[48:51]
	v_mfma_f32_16x16x32_bf16 v[36:39], v[172:175], v[196:199], v[36:39]
	v_mfma_f32_16x16x32_bf16 v[32:35], v[180:183], v[196:199], v[32:35]
	v_mfma_f32_16x16x32_bf16 v[20:23], v[172:175], v[204:207], v[20:23]
	v_mfma_f32_16x16x32_bf16 v[16:19], v[180:183], v[204:207], v[16:19]
	v_mfma_f32_16x16x32_bf16 v[4:7], v[172:175], v[228:231], v[4:7]
	v_mfma_f32_16x16x32_bf16 v[0:3], v[180:183], v[228:231], v[0:3]
	s_barrier
	s_add_i32 s10, s10, 2
	s_add_i32 s8, s8, 0x8000
	s_add_i32 s9, s9, 0x8000

.Lpeel_p5:
	s_waitcnt lgkmcnt(0)
	s_add_i32 s53, s37, 0xfff84000
	s_cmp_eq_u32 s52, 28
	s_cselect_b32 s56, s4, s53
	s_cselect_b32 s55, s5, s51
	s_or_b32 s53, s56, 0x4000
	s_mov_b32 m0, s41
	s_nop 0
	buffer_load_dwordx4 v166, s[24:27], s37 offen lds
	s_nop 0
	s_mov_b32 m0, s42
	s_nop 0
	buffer_load_dwordx4 v167, s[24:27], s37 offen lds
	s_waitcnt vmcnt(24) lgkmcnt(0)
	s_barrier
	s_waitcnt lgkmcnt(7)
	v_mfma_f32_16x16x32_bf16 v[148:151], v[152:155], v[190:193], 0
	v_mfma_f32_16x16x32_bf16 v[140:143], v[160:163], v[190:193], 0
	s_waitcnt lgkmcnt(5)
	v_mfma_f32_16x16x32_bf16 v[132:135], v[152:155], v[198:201], 0
	v_mfma_f32_16x16x32_bf16 v[124:127], v[160:163], v[198:201], 0
	s_waitcnt lgkmcnt(3)
	v_mfma_f32_16x16x32_bf16 v[116:119], v[152:155], v[220:223], 0
	v_mfma_f32_16x16x32_bf16 v[108:111], v[160:163], v[220:223], 0
	s_waitcnt lgkmcnt(1)
	v_mfma_f32_16x16x32_bf16 v[76:79], v[152:155], v[228:231], 0
	v_mfma_f32_16x16x32_bf16 v[68:71], v[160:163], v[228:231], 0
	v_mfma_f32_16x16x32_bf16 v[148:151], v[156:159], v[194:197], v[148:151]
	v_mfma_f32_16x16x32_bf16 v[140:143], v[170:173], v[194:197], v[140:143]
	v_mfma_f32_16x16x32_bf16 v[132:135], v[156:159], v[202:205], v[132:135]
	v_mfma_f32_16x16x32_bf16 v[124:127], v[170:173], v[202:205], v[124:127]
	v_mfma_f32_16x16x32_bf16 v[116:119], v[156:159], v[224:227], v[116:119]
	v_mfma_f32_16x16x32_bf16 v[108:111], v[170:173], v[224:227], v[108:111]
	s_waitcnt lgkmcnt(0)
	v_mfma_f32_16x16x32_bf16 v[76:79], v[156:159], v[240:243], v[76:79]
	v_mfma_f32_16x16x32_bf16 v[68:71], v[170:173], v[240:243], v[68:71]
	v_mfma_f32_16x16x32_bf16 v[144:147], v[174:177], v[190:193], 0
	v_mfma_f32_16x16x32_bf16 v[136:139], v[182:185], v[190:193], 0
	v_mfma_f32_16x16x32_bf16 v[128:131], v[174:177], v[198:201], 0
	v_mfma_f32_16x16x32_bf16 v[120:123], v[182:185], v[198:201], 0
	v_mfma_f32_16x16x32_bf16 v[112:115], v[174:177], v[220:223], 0
	v_mfma_f32_16x16x32_bf16 v[104:107], v[182:185], v[220:223], 0
	v_mfma_f32_16x16x32_bf16 v[72:75], v[174:177], v[228:231], 0
	v_mfma_f32_16x16x32_bf16 v[64:67], v[182:185], v[228:231], 0
	v_mfma_f32_16x16x32_bf16 v[144:147], v[178:181], v[194:197], v[144:147]
	v_mfma_f32_16x16x32_bf16 v[136:139], v[186:189], v[194:197], v[136:139]
	v_mfma_f32_16x16x32_bf16 v[128:131], v[178:181], v[202:205], v[128:131]
	v_mfma_f32_16x16x32_bf16 v[120:123], v[186:189], v[202:205], v[120:123]
	v_mfma_f32_16x16x32_bf16 v[112:115], v[178:181], v[224:227], v[112:115]
	v_mfma_f32_16x16x32_bf16 v[104:107], v[186:189], v[224:227], v[104:107]
	v_mfma_f32_16x16x32_bf16 v[72:75], v[178:181], v[240:243], v[72:75]
	v_mfma_f32_16x16x32_bf16 v[64:67], v[186:189], v[240:243], v[64:67]
	s_barrier
	ds_read_b128 v[190:193], v169 offset:16384
	ds_read_b128 v[194:197], v169 offset:17408
	ds_read_b128 v[198:201], v169 offset:18432
	ds_read_b128 v[202:205], v169 offset:19456
	ds_read_b128 v[220:223], v169 offset:20480
	ds_read_b128 v[224:227], v169 offset:21504
	ds_read_b128 v[228:231], v169 offset:22528
	ds_read_b128 v[240:243], v169 offset:23552
	s_mov_b32 m0, s7
	s_nop 0
	buffer_load_dwordx4 v166, s[28:31], s55 offen lds
	s_add_i32 s57, s55, 0x80000
	s_mov_b32 m0, s8
	s_nop 0
	buffer_load_dwordx4 v167, s[28:31], s55 offen lds
	s_nop 0
	s_mov_b32 m0, s9
	s_nop 0
	buffer_load_dwordx4 v166, s[28:31], s57 offen lds
	s_nop 0
	s_mov_b32 m0, s10
	s_nop 0
	buffer_load_dwordx4 v167, s[28:31], s57 offen lds
	s_nop 0
	s_mov_b32 m0, s6
	s_nop 0
	buffer_load_dwordx4 v166, s[24:27], s56 offen lds
	s_nop 0
	s_mov_b32 m0, s11
	s_nop 0
	buffer_load_dwordx4 v167, s[24:27], s56 offen lds
	s_waitcnt vmcnt(24) lgkmcnt(0)
	s_barrier
	s_waitcnt lgkmcnt(7)
	v_mfma_f32_16x16x32_bf16 v[60:63], v[152:155], v[190:193], 0
	v_mfma_f32_16x16x32_bf16 v[52:55], v[160:163], v[190:193], 0
	s_waitcnt lgkmcnt(5)
	v_mfma_f32_16x16x32_bf16 v[44:47], v[152:155], v[198:201], 0
	v_mfma_f32_16x16x32_bf16 v[36:39], v[160:163], v[198:201], 0
	s_waitcnt lgkmcnt(3)
	v_mfma_f32_16x16x32_bf16 v[28:31], v[152:155], v[220:223], 0
	v_mfma_f32_16x16x32_bf16 v[20:23], v[160:163], v[220:223], 0
	s_waitcnt lgkmcnt(1)
	v_mfma_f32_16x16x32_bf16 v[12:15], v[152:155], v[228:231], 0
	v_mfma_f32_16x16x32_bf16 v[4:7], v[160:163], v[228:231], 0
	v_mfma_f32_16x16x32_bf16 v[60:63], v[156:159], v[194:197], v[60:63]
	v_mfma_f32_16x16x32_bf16 v[52:55], v[170:173], v[194:197], v[52:55]
	v_mfma_f32_16x16x32_bf16 v[44:47], v[156:159], v[202:205], v[44:47]
	v_mfma_f32_16x16x32_bf16 v[36:39], v[170:173], v[202:205], v[36:39]
	v_mfma_f32_16x16x32_bf16 v[28:31], v[156:159], v[224:227], v[28:31]
	v_mfma_f32_16x16x32_bf16 v[20:23], v[170:173], v[224:227], v[20:23]
	s_waitcnt lgkmcnt(0)
	v_mfma_f32_16x16x32_bf16 v[12:15], v[156:159], v[240:243], v[12:15]
	v_mfma_f32_16x16x32_bf16 v[4:7], v[170:173], v[240:243], v[4:7]
	v_mfma_f32_16x16x32_bf16 v[56:59], v[174:177], v[190:193], 0
	v_mfma_f32_16x16x32_bf16 v[48:51], v[182:185], v[190:193], 0
	v_mfma_f32_16x16x32_bf16 v[40:43], v[174:177], v[198:201], 0
	v_mfma_f32_16x16x32_bf16 v[32:35], v[182:185], v[198:201], 0
	v_mfma_f32_16x16x32_bf16 v[24:27], v[174:177], v[220:223], 0
	v_mfma_f32_16x16x32_bf16 v[16:19], v[182:185], v[220:223], 0
	v_mfma_f32_16x16x32_bf16 v[8:11], v[174:177], v[228:231], 0
	v_mfma_f32_16x16x32_bf16 v[0:3], v[182:185], v[228:231], 0
	v_mfma_f32_16x16x32_bf16 v[56:59], v[178:181], v[194:197], v[56:59]
	v_mfma_f32_16x16x32_bf16 v[48:51], v[186:189], v[194:197], v[48:51]
	v_mfma_f32_16x16x32_bf16 v[40:43], v[178:181], v[202:205], v[40:43]
	v_mfma_f32_16x16x32_bf16 v[32:35], v[186:189], v[202:205], v[32:35]
	v_mfma_f32_16x16x32_bf16 v[24:27], v[178:181], v[224:227], v[24:27]
	v_mfma_f32_16x16x32_bf16 v[16:19], v[186:189], v[224:227], v[16:19]
	v_mfma_f32_16x16x32_bf16 v[8:11], v[178:181], v[240:243], v[8:11]
	v_mfma_f32_16x16x32_bf16 v[0:3], v[186:189], v[240:243], v[0:3]
	s_barrier
	v_add_u32_e32 v164, 0x18000, v168
	ds_read_b128 v[152:155], v164
	ds_read_b128 v[156:159], v164 offset:1024
	ds_read_b128 v[160:163], v164 offset:2048
	ds_read_b128 v[170:173], v164 offset:3072
	v_add_u32_e32 v164, 0x1c000, v168
	ds_read_b128 v[174:177], v164
	ds_read_b128 v[178:181], v164 offset:1024
	ds_read_b128 v[182:185], v164 offset:2048
	ds_read_b128 v[186:189], v164 offset:3072
	ds_read_b128 v[190:193], v169 offset:32768
	ds_read_b128 v[194:197], v169 offset:33792
	ds_read_b128 v[198:201], v169 offset:34816
	ds_read_b128 v[202:205], v169 offset:35840
	ds_read_b128 v[220:223], v169 offset:36864
	ds_read_b128 v[224:227], v169 offset:37888
	ds_read_b128 v[228:231], v169 offset:38912
	ds_read_b128 v[240:243], v169 offset:39936
	s_add_i32 s56, s56, 0x80000
	s_mov_b32 m0, s12
	s_nop 0
	buffer_load_dwordx4 v166, s[24:27], s56 offen lds
	s_nop 0
	s_mov_b32 m0, s13
	s_nop 0
	buffer_load_dwordx4 v167, s[24:27], s56 offen lds
	s_waitcnt vmcnt(8) lgkmcnt(0)
	s_barrier
	s_waitcnt lgkmcnt(7)
	v_mfma_f32_16x16x32_bf16 v[148:151], v[152:155], v[190:193], v[148:151]
	v_mfma_f32_16x16x32_bf16 v[140:143], v[160:163], v[190:193], v[140:143]
	s_waitcnt lgkmcnt(5)
	v_mfma_f32_16x16x32_bf16 v[132:135], v[152:155], v[198:201], v[132:135]
	v_mfma_f32_16x16x32_bf16 v[124:127], v[160:163], v[198:201], v[124:127]
	s_waitcnt lgkmcnt(3)
	v_mfma_f32_16x16x32_bf16 v[116:119], v[152:155], v[220:223], v[116:119]
	v_mfma_f32_16x16x32_bf16 v[108:111], v[160:163], v[220:223], v[108:111]
	s_waitcnt lgkmcnt(1)
	v_mfma_f32_16x16x32_bf16 v[76:79], v[152:155], v[228:231], v[76:79]
	v_mfma_f32_16x16x32_bf16 v[68:71], v[160:163], v[228:231], v[68:71]
	v_mfma_f32_16x16x32_bf16 v[148:151], v[156:159], v[194:197], v[148:151]
	v_mfma_f32_16x16x32_bf16 v[140:143], v[170:173], v[194:197], v[140:143]
	v_mfma_f32_16x16x32_bf16 v[132:135], v[156:159], v[202:205], v[132:135]
	v_mfma_f32_16x16x32_bf16 v[124:127], v[170:173], v[202:205], v[124:127]
	v_mfma_f32_16x16x32_bf16 v[116:119], v[156:159], v[224:227], v[116:119]
	v_mfma_f32_16x16x32_bf16 v[108:111], v[170:173], v[224:227], v[108:111]
	s_waitcnt lgkmcnt(0)
	v_mfma_f32_16x16x32_bf16 v[76:79], v[156:159], v[240:243], v[76:79]
	v_mfma_f32_16x16x32_bf16 v[68:71], v[170:173], v[240:243], v[68:71]
	v_mfma_f32_16x16x32_bf16 v[144:147], v[174:177], v[190:193], v[144:147]
	v_mfma_f32_16x16x32_bf16 v[136:139], v[182:185], v[190:193], v[136:139]
	v_mfma_f32_16x16x32_bf16 v[128:131], v[174:177], v[198:201], v[128:131]
	v_mfma_f32_16x16x32_bf16 v[120:123], v[182:185], v[198:201], v[120:123]
	v_mfma_f32_16x16x32_bf16 v[112:115], v[174:177], v[220:223], v[112:115]
	v_mfma_f32_16x16x32_bf16 v[104:107], v[182:185], v[220:223], v[104:107]
	v_mfma_f32_16x16x32_bf16 v[72:75], v[174:177], v[228:231], v[72:75]
	v_mfma_f32_16x16x32_bf16 v[64:67], v[182:185], v[228:231], v[64:67]
	v_mfma_f32_16x16x32_bf16 v[144:147], v[178:181], v[194:197], v[144:147]
	v_mfma_f32_16x16x32_bf16 v[136:139], v[186:189], v[194:197], v[136:139]
	v_mfma_f32_16x16x32_bf16 v[128:131], v[178:181], v[202:205], v[128:131]
	v_mfma_f32_16x16x32_bf16 v[120:123], v[186:189], v[202:205], v[120:123]
	v_mfma_f32_16x16x32_bf16 v[112:115], v[178:181], v[224:227], v[112:115]
	v_mfma_f32_16x16x32_bf16 v[104:107], v[186:189], v[224:227], v[104:107]
	v_mfma_f32_16x16x32_bf16 v[72:75], v[178:181], v[240:243], v[72:75]
	v_mfma_f32_16x16x32_bf16 v[64:67], v[186:189], v[240:243], v[64:67]
	s_barrier
	ds_read_b128 v[190:193], v169 offset:49152
	ds_read_b128 v[194:197], v169 offset:50176
	ds_read_b128 v[198:201], v169 offset:51200
	ds_read_b128 v[202:205], v169 offset:52224
	ds_read_b128 v[220:223], v169 offset:53248
	ds_read_b128 v[224:227], v169 offset:54272
	ds_read_b128 v[228:231], v169 offset:55296
	ds_read_b128 v[240:243], v169 offset:56320
	s_or_b32 s56, s55, 0x4000
	s_mov_b32 m0, s16
	s_nop 0
	buffer_load_dwordx4 v166, s[28:31], s56 offen lds
	s_add_i32 s55, s55, 0x84000
	s_mov_b32 m0, s17
	s_nop 0
	buffer_load_dwordx4 v167, s[28:31], s56 offen lds
	s_nop 0
	s_mov_b32 m0, s34
	s_nop 0
	buffer_load_dwordx4 v166, s[28:31], s55 offen lds
	s_nop 0
	s_mov_b32 m0, s40
	s_nop 0
	buffer_load_dwordx4 v167, s[28:31], s55 offen lds
	s_nop 0
	s_mov_b32 m0, s18
	s_nop 0
	buffer_load_dwordx4 v166, s[24:27], s53 offen lds
	s_nop 0
	s_mov_b32 m0, s19
	s_nop 0
	buffer_load_dwordx4 v167, s[24:27], s53 offen lds
	s_waitcnt vmcnt(8) lgkmcnt(0)
	s_barrier
	s_waitcnt lgkmcnt(7)
	v_mfma_f32_16x16x32_bf16 v[60:63], v[152:155], v[190:193], v[60:63]
	v_mfma_f32_16x16x32_bf16 v[52:55], v[160:163], v[190:193], v[52:55]
	s_waitcnt lgkmcnt(5)
	v_mfma_f32_16x16x32_bf16 v[44:47], v[152:155], v[198:201], v[44:47]
	v_mfma_f32_16x16x32_bf16 v[36:39], v[160:163], v[198:201], v[36:39]
	s_waitcnt lgkmcnt(3)
	v_mfma_f32_16x16x32_bf16 v[28:31], v[152:155], v[220:223], v[28:31]
	v_mfma_f32_16x16x32_bf16 v[20:23], v[160:163], v[220:223], v[20:23]
	s_waitcnt lgkmcnt(1)
	v_mfma_f32_16x16x32_bf16 v[12:15], v[152:155], v[228:231], v[12:15]
	v_mfma_f32_16x16x32_bf16 v[4:7], v[160:163], v[228:231], v[4:7]
	v_mfma_f32_16x16x32_bf16 v[60:63], v[156:159], v[194:197], v[60:63]
	v_mfma_f32_16x16x32_bf16 v[52:55], v[170:173], v[194:197], v[52:55]
	v_mfma_f32_16x16x32_bf16 v[44:47], v[156:159], v[202:205], v[44:47]
	v_mfma_f32_16x16x32_bf16 v[36:39], v[170:173], v[202:205], v[36:39]
	v_mfma_f32_16x16x32_bf16 v[28:31], v[156:159], v[224:227], v[28:31]
	v_mfma_f32_16x16x32_bf16 v[20:23], v[170:173], v[224:227], v[20:23]
	s_waitcnt lgkmcnt(0)
	v_mfma_f32_16x16x32_bf16 v[12:15], v[156:159], v[240:243], v[12:15]
	v_mfma_f32_16x16x32_bf16 v[4:7], v[170:173], v[240:243], v[4:7]
	v_mfma_f32_16x16x32_bf16 v[56:59], v[174:177], v[190:193], v[56:59]
	v_mfma_f32_16x16x32_bf16 v[48:51], v[182:185], v[190:193], v[48:51]
	v_mfma_f32_16x16x32_bf16 v[40:43], v[174:177], v[198:201], v[40:43]
	v_mfma_f32_16x16x32_bf16 v[32:35], v[182:185], v[198:201], v[32:35]
	v_mfma_f32_16x16x32_bf16 v[24:27], v[174:177], v[220:223], v[24:27]
	v_mfma_f32_16x16x32_bf16 v[16:19], v[182:185], v[220:223], v[16:19]
	v_mfma_f32_16x16x32_bf16 v[8:11], v[174:177], v[228:231], v[8:11]
	v_mfma_f32_16x16x32_bf16 v[0:3], v[182:185], v[228:231], v[0:3]
	v_mfma_f32_16x16x32_bf16 v[56:59], v[178:181], v[194:197], v[56:59]
	v_mfma_f32_16x16x32_bf16 v[48:51], v[186:189], v[194:197], v[48:51]
	v_mfma_f32_16x16x32_bf16 v[40:43], v[178:181], v[202:205], v[40:43]
	v_mfma_f32_16x16x32_bf16 v[32:35], v[186:189], v[202:205], v[32:35]
	v_mfma_f32_16x16x32_bf16 v[24:27], v[178:181], v[224:227], v[24:27]
	v_mfma_f32_16x16x32_bf16 v[16:19], v[186:189], v[224:227], v[16:19]
	v_mfma_f32_16x16x32_bf16 v[8:11], v[178:181], v[240:243], v[8:11]
	v_mfma_f32_16x16x32_bf16 v[0:3], v[186:189], v[240:243], v[0:3]
	s_barrier
	s_add_i32 s52, s52, 2
	s_add_i32 s37, s37, 0x8000
	s_add_i32 s51, s51, 0x8000

.Lab_p5:
	s_nop 0
	v_cvt_f32_u32_e32 v171, v85
	v_cvt_f32_u32_e32 v170, v84
	v_fmac_f32_e32 v170, 0x4f800000, v171
	v_fmamk_f32 v170, v170, 0x30000000, v234
	v_rsq_f32_e32 v178, v170
	s_nop 0
	v_mul_f32_e32 v174, 0xbfb8aa3b, v178
	v_pk_mul_f32 v[172:173], v[150:151], v[174:175] op_sel_hi:[1,0]
	v_pk_mul_f32 v[170:171], v[148:149], v[174:175] op_sel_hi:[1,0]
	v_pk_mul_f32 v[176:177], v[142:143], v[174:175] op_sel_hi:[1,0]
	v_pk_mul_f32 v[174:175], v[140:141], v[174:175] op_sel_hi:[1,0]
	v_mul_f32_e32 v178, v178, v178
	v_pk_mul_f32 v[180:181], v[146:147], v[178:179] op_sel_hi:[1,0]
	v_exp_f32_e32 v170, v170
	v_exp_f32_e32 v174, v174
	v_exp_f32_e32 v171, v171
	v_exp_f32_e32 v175, v175
	v_exp_f32_e32 v172, v172
	v_exp_f32_e32 v176, v176
	v_exp_f32_e32 v173, v173
	v_exp_f32_e32 v177, v177
	v_pk_mul_f32 v[182:183], v[144:145], v[178:179] op_sel_hi:[1,0]
	v_pk_add_f32 v[144:145], v[170:171], 1.0 op_sel_hi:[1,0]
	v_pk_add_f32 v[146:147], v[172:173], 1.0 op_sel_hi:[1,0]
	v_pk_add_f32 v[150:151], v[176:177], 1.0 op_sel_hi:[1,0]
	v_pk_add_f32 v[148:149], v[174:175], 1.0 op_sel_hi:[1,0]
	v_pk_mul_f32 v[138:139], v[138:139], v[178:179] op_sel_hi:[1,0]
	v_pk_mul_f32 v[136:137], v[136:137], v[178:179] op_sel_hi:[1,0]
	v_rcp_f32_e32 v144, v144
	v_rcp_f32_e32 v148, v148
	v_rcp_f32_e32 v145, v145
	v_rcp_f32_e32 v149, v149
	v_rcp_f32_e32 v146, v146
	v_rcp_f32_e32 v150, v150
	v_rcp_f32_e32 v147, v147
	v_rcp_f32_e32 v151, v151
	s_nop 0
	v_pk_mul_f32 v[140:141], v[180:181], v[146:147]
	v_pk_mul_f32 v[142:143], v[182:183], v[144:145]
	v_pk_mul_f32 v[144:145], v[138:139], v[150:151]
	v_pk_mul_f32 v[138:139], v[136:137], v[148:149]
	v_cvt_pk_bf16_f32 v136, v142, v143
	v_cvt_pk_bf16_f32 v137, v140, v141
	v_cvt_pk_bf16_f32 v138, v138, v139
	v_cvt_pk_bf16_f32 v139, v144, v145
	v_lshl_add_u64 v[140:141], s[36:37], 0, v[82:83]
	global_store_dwordx4 v[140:141], v[136:139], off nt
	s_nop 0
	s_nop 0
	v_cvt_f32_u32_e32 v136, v87
	v_cvt_f32_u32_e32 v137, v86
	v_fmac_f32_e32 v137, 0x4f800000, v136
	v_fmamk_f32 v136, v137, 0x30000000, v234
	v_rsq_f32_e32 v144, v136
	s_nop 0
	v_mul_f32_e32 v140, 0xbfb8aa3b, v144
	v_pk_mul_f32 v[138:139], v[134:135], v[140:141] op_sel_hi:[1,0]
	v_pk_mul_f32 v[136:137], v[132:133], v[140:141] op_sel_hi:[1,0]
	v_pk_mul_f32 v[142:143], v[126:127], v[140:141] op_sel_hi:[1,0]
	v_pk_mul_f32 v[140:141], v[124:125], v[140:141] op_sel_hi:[1,0]
	v_mul_f32_e32 v144, v144, v144
	v_pk_mul_f32 v[146:147], v[130:131], v[144:145] op_sel_hi:[1,0]
	v_exp_f32_e32 v136, v136
	v_exp_f32_e32 v140, v140
	v_exp_f32_e32 v137, v137
	v_exp_f32_e32 v141, v141
	v_exp_f32_e32 v138, v138
	v_exp_f32_e32 v142, v142
	v_exp_f32_e32 v139, v139
	v_exp_f32_e32 v143, v143
	v_pk_mul_f32 v[148:149], v[128:129], v[144:145] op_sel_hi:[1,0]
	v_pk_add_f32 v[128:129], v[136:137], 1.0 op_sel_hi:[1,0]
	v_pk_add_f32 v[130:131], v[138:139], 1.0 op_sel_hi:[1,0]
	v_pk_add_f32 v[134:135], v[142:143], 1.0 op_sel_hi:[1,0]
	v_pk_add_f32 v[132:133], v[140:141], 1.0 op_sel_hi:[1,0]
	v_pk_mul_f32 v[122:123], v[122:123], v[144:145] op_sel_hi:[1,0]
	v_pk_mul_f32 v[120:121], v[120:121], v[144:145] op_sel_hi:[1,0]
	v_rcp_f32_e32 v128, v128
	v_rcp_f32_e32 v132, v132
	v_rcp_f32_e32 v129, v129
	v_rcp_f32_e32 v133, v133
	v_rcp_f32_e32 v130, v130
	v_rcp_f32_e32 v134, v134
	v_rcp_f32_e32 v131, v131
	v_rcp_f32_e32 v135, v135
	s_nop 0
	v_pk_mul_f32 v[124:125], v[146:147], v[130:131]
	v_pk_mul_f32 v[126:127], v[148:149], v[128:129]
	v_pk_mul_f32 v[128:129], v[122:123], v[134:135]
	v_pk_mul_f32 v[122:123], v[120:121], v[132:133]
	v_cvt_pk_bf16_f32 v120, v126, v127
	v_cvt_pk_bf16_f32 v121, v124, v125
	v_cvt_pk_bf16_f32 v122, v122, v123
	v_cvt_pk_bf16_f32 v123, v128, v129
	v_lshl_add_u64 v[124:125], s[4:5], 0, v[82:83]
	global_store_dwordx4 v[124:125], v[120:123], off nt
	s_or_b32 s4, s33, 0x1000
	s_add_u32 s4, s20, s4
	s_nop 0
	v_cvt_f32_u32_e32 v120, v89
	v_cvt_f32_u32_e32 v121, v88
	s_addc_u32 s5, s68, 0
	v_fmac_f32_e32 v121, 0x4f800000, v120
	v_fmamk_f32 v120, v121, 0x30000000, v234
	v_rsq_f32_e32 v128, v120
	s_nop 0
	v_mul_f32_e32 v124, 0xbfb8aa3b, v128
	v_pk_mul_f32 v[122:123], v[118:119], v[124:125] op_sel_hi:[1,0]
	v_pk_mul_f32 v[120:121], v[116:117], v[124:125] op_sel_hi:[1,0]
	v_pk_mul_f32 v[126:127], v[110:111], v[124:125] op_sel_hi:[1,0]
	v_pk_mul_f32 v[124:125], v[108:109], v[124:125] op_sel_hi:[1,0]
	v_mul_f32_e32 v128, v128, v128
	v_pk_mul_f32 v[130:131], v[114:115], v[128:129] op_sel_hi:[1,0]
	v_exp_f32_e32 v120, v120
	v_exp_f32_e32 v124, v124
	v_exp_f32_e32 v121, v121
	v_exp_f32_e32 v125, v125
	v_exp_f32_e32 v122, v122
	v_exp_f32_e32 v126, v126
	v_exp_f32_e32 v123, v123
	v_exp_f32_e32 v127, v127
	v_pk_mul_f32 v[132:133], v[112:113], v[128:129] op_sel_hi:[1,0]
	v_pk_add_f32 v[112:113], v[120:121], 1.0 op_sel_hi:[1,0]
	v_pk_add_f32 v[114:115], v[122:123], 1.0 op_sel_hi:[1,0]
	v_pk_add_f32 v[118:119], v[126:127], 1.0 op_sel_hi:[1,0]
	v_pk_add_f32 v[116:117], v[124:125], 1.0 op_sel_hi:[1,0]
	v_pk_mul_f32 v[106:107], v[106:107], v[128:129] op_sel_hi:[1,0]
	v_pk_mul_f32 v[104:105], v[104:105], v[128:129] op_sel_hi:[1,0]
	v_rcp_f32_e32 v112, v112
	v_rcp_f32_e32 v116, v116
	v_rcp_f32_e32 v113, v113
	v_rcp_f32_e32 v117, v117
	v_rcp_f32_e32 v114, v114
	v_rcp_f32_e32 v118, v118
	v_rcp_f32_e32 v115, v115
	v_rcp_f32_e32 v119, v119
	s_nop 0
	v_pk_mul_f32 v[108:109], v[130:131], v[114:115]
	v_pk_mul_f32 v[110:111], v[132:133], v[112:113]
	v_pk_mul_f32 v[112:113], v[106:107], v[118:119]
	v_pk_mul_f32 v[106:107], v[104:105], v[116:117]
	v_cvt_pk_bf16_f32 v104, v110, v111
	v_cvt_pk_bf16_f32 v105, v108, v109
	v_cvt_pk_bf16_f32 v106, v106, v107
	v_cvt_pk_bf16_f32 v107, v112, v113
	v_lshl_add_u64 v[108:109], s[4:5], 0, v[82:83]
	global_store_dwordx4 v[108:109], v[104:107], off nt
	s_or_b32 s4, s33, 0x1800
	s_add_u32 s4, s20, s4
	s_nop 0
	v_cvt_f32_u32_e32 v104, v91
	v_cvt_f32_u32_e32 v105, v90
	s_addc_u32 s5, s68, 0
	v_fmac_f32_e32 v105, 0x4f800000, v104
	v_fmamk_f32 v104, v105, 0x30000000, v234
	v_rsq_f32_e32 v112, v104
	s_nop 0
	v_mul_f32_e32 v108, 0xbfb8aa3b, v112
	v_pk_mul_f32 v[106:107], v[78:79], v[108:109] op_sel_hi:[1,0]
	v_pk_mul_f32 v[104:105], v[76:77], v[108:109] op_sel_hi:[1,0]
	v_pk_mul_f32 v[110:111], v[70:71], v[108:109] op_sel_hi:[1,0]
	v_pk_mul_f32 v[108:109], v[68:69], v[108:109] op_sel_hi:[1,0]
	v_mul_f32_e32 v112, v112, v112
	v_pk_mul_f32 v[114:115], v[74:75], v[112:113] op_sel_hi:[1,0]
	v_exp_f32_e32 v104, v104
	v_exp_f32_e32 v108, v108
	v_exp_f32_e32 v105, v105
	v_exp_f32_e32 v109, v109
	v_exp_f32_e32 v106, v106
	v_exp_f32_e32 v110, v110
	v_exp_f32_e32 v107, v107
	v_exp_f32_e32 v111, v111
	v_pk_mul_f32 v[116:117], v[72:73], v[112:113] op_sel_hi:[1,0]
	v_pk_add_f32 v[72:73], v[104:105], 1.0 op_sel_hi:[1,0]
	v_pk_add_f32 v[74:75], v[106:107], 1.0 op_sel_hi:[1,0]
	v_pk_add_f32 v[78:79], v[110:111], 1.0 op_sel_hi:[1,0]
	v_pk_add_f32 v[76:77], v[108:109], 1.0 op_sel_hi:[1,0]
	v_pk_mul_f32 v[66:67], v[66:67], v[112:113] op_sel_hi:[1,0]
	v_pk_mul_f32 v[64:65], v[64:65], v[112:113] op_sel_hi:[1,0]
	v_rcp_f32_e32 v72, v72
	v_rcp_f32_e32 v76, v76
	v_rcp_f32_e32 v73, v73
	v_rcp_f32_e32 v77, v77
	v_rcp_f32_e32 v74, v74
	v_rcp_f32_e32 v78, v78
	v_rcp_f32_e32 v75, v75
	v_rcp_f32_e32 v79, v79
	s_nop 0
	v_pk_mul_f32 v[68:69], v[114:115], v[74:75]
	v_pk_mul_f32 v[70:71], v[116:117], v[72:73]
	v_pk_mul_f32 v[72:73], v[66:67], v[78:79]
	v_pk_mul_f32 v[66:67], v[64:65], v[76:77]
	v_cvt_pk_bf16_f32 v64, v70, v71
	v_cvt_pk_bf16_f32 v65, v68, v69
	v_cvt_pk_bf16_f32 v66, v66, v67
	v_cvt_pk_bf16_f32 v67, v72, v73
	v_lshl_add_u64 v[68:69], s[4:5], 0, v[82:83]
	global_store_dwordx4 v[68:69], v[64:67], off nt
	s_add_i32 s4, s33, 0x160000
	s_add_u32 s4, s20, s4
	s_nop 0
	v_cvt_f32_u32_e32 v64, v93
	v_cvt_f32_u32_e32 v65, v92
	s_addc_u32 s5, s68, 0
	v_fmac_f32_e32 v65, 0x4f800000, v64
	v_fmamk_f32 v64, v65, 0x30000000, v234
	v_rsq_f32_e32 v72, v64
	s_nop 0
	v_mul_f32_e32 v68, 0xbfb8aa3b, v72
	v_pk_mul_f32 v[66:67], v[62:63], v[68:69] op_sel_hi:[1,0]
	v_pk_mul_f32 v[64:65], v[60:61], v[68:69] op_sel_hi:[1,0]
	v_pk_mul_f32 v[70:71], v[54:55], v[68:69] op_sel_hi:[1,0]
	v_pk_mul_f32 v[68:69], v[52:53], v[68:69] op_sel_hi:[1,0]
	v_mul_f32_e32 v72, v72, v72
	v_pk_mul_f32 v[74:75], v[58:59], v[72:73] op_sel_hi:[1,0]
	v_exp_f32_e32 v64, v64
	v_exp_f32_e32 v68, v68
	v_exp_f32_e32 v65, v65
	v_exp_f32_e32 v69, v69
	v_exp_f32_e32 v66, v66
	v_exp_f32_e32 v70, v70
	v_exp_f32_e32 v67, v67
	v_exp_f32_e32 v71, v71
	v_pk_mul_f32 v[76:77], v[56:57], v[72:73] op_sel_hi:[1,0]
	v_pk_add_f32 v[56:57], v[64:65], 1.0 op_sel_hi:[1,0]
	v_pk_add_f32 v[58:59], v[66:67], 1.0 op_sel_hi:[1,0]
	v_pk_add_f32 v[62:63], v[70:71], 1.0 op_sel_hi:[1,0]
	v_pk_add_f32 v[60:61], v[68:69], 1.0 op_sel_hi:[1,0]
	v_pk_mul_f32 v[50:51], v[50:51], v[72:73] op_sel_hi:[1,0]
	v_pk_mul_f32 v[48:49], v[48:49], v[72:73] op_sel_hi:[1,0]
	v_rcp_f32_e32 v56, v56
	v_rcp_f32_e32 v60, v60
	v_rcp_f32_e32 v57, v57
	v_rcp_f32_e32 v61, v61
	v_rcp_f32_e32 v58, v58
	v_rcp_f32_e32 v62, v62
	v_rcp_f32_e32 v59, v59
	v_rcp_f32_e32 v63, v63
	s_nop 0
	v_pk_mul_f32 v[52:53], v[74:75], v[58:59]
	v_pk_mul_f32 v[54:55], v[76:77], v[56:57]
	v_pk_mul_f32 v[56:57], v[50:51], v[62:63]
	v_pk_mul_f32 v[50:51], v[48:49], v[60:61]
	v_cvt_pk_bf16_f32 v48, v54, v55
	v_cvt_pk_bf16_f32 v49, v52, v53
	v_cvt_pk_bf16_f32 v50, v50, v51
	v_cvt_pk_bf16_f32 v51, v56, v57
	v_lshl_add_u64 v[52:53], s[4:5], 0, v[82:83]
	global_store_dwordx4 v[52:53], v[48:51], off nt
	s_add_i32 s4, s33, 0x160800
	s_add_u32 s4, s20, s4
	s_nop 0
	v_cvt_f32_u32_e32 v48, v95
	v_cvt_f32_u32_e32 v49, v94
	s_addc_u32 s5, s68, 0
	v_fmac_f32_e32 v49, 0x4f800000, v48
	v_fmamk_f32 v48, v49, 0x30000000, v234
	v_rsq_f32_e32 v56, v48
	s_nop 0
	v_mul_f32_e32 v52, 0xbfb8aa3b, v56
	v_pk_mul_f32 v[50:51], v[46:47], v[52:53] op_sel_hi:[1,0]
	v_pk_mul_f32 v[48:49], v[44:45], v[52:53] op_sel_hi:[1,0]
	v_pk_mul_f32 v[54:55], v[38:39], v[52:53] op_sel_hi:[1,0]
	v_pk_mul_f32 v[52:53], v[36:37], v[52:53] op_sel_hi:[1,0]
	v_mul_f32_e32 v56, v56, v56
	v_pk_mul_f32 v[58:59], v[42:43], v[56:57] op_sel_hi:[1,0]
	v_exp_f32_e32 v48, v48
	v_exp_f32_e32 v52, v52
	v_exp_f32_e32 v49, v49
	v_exp_f32_e32 v53, v53
	v_exp_f32_e32 v50, v50
	v_exp_f32_e32 v54, v54
	v_exp_f32_e32 v51, v51
	v_exp_f32_e32 v55, v55
	v_pk_mul_f32 v[60:61], v[40:41], v[56:57] op_sel_hi:[1,0]
	v_pk_add_f32 v[40:41], v[48:49], 1.0 op_sel_hi:[1,0]
	v_pk_add_f32 v[42:43], v[50:51], 1.0 op_sel_hi:[1,0]
	v_pk_add_f32 v[46:47], v[54:55], 1.0 op_sel_hi:[1,0]
	v_pk_add_f32 v[44:45], v[52:53], 1.0 op_sel_hi:[1,0]
	v_pk_mul_f32 v[34:35], v[34:35], v[56:57] op_sel_hi:[1,0]
	v_pk_mul_f32 v[32:33], v[32:33], v[56:57] op_sel_hi:[1,0]
	v_rcp_f32_e32 v40, v40
	v_rcp_f32_e32 v44, v44
	v_rcp_f32_e32 v41, v41
	v_rcp_f32_e32 v45, v45
	v_rcp_f32_e32 v42, v42
	v_rcp_f32_e32 v46, v46
	v_rcp_f32_e32 v43, v43
	v_rcp_f32_e32 v47, v47
	s_nop 0
	v_pk_mul_f32 v[36:37], v[58:59], v[42:43]
	v_pk_mul_f32 v[38:39], v[60:61], v[40:41]
	v_pk_mul_f32 v[40:41], v[34:35], v[46:47]
	v_pk_mul_f32 v[34:35], v[32:33], v[44:45]
	v_cvt_pk_bf16_f32 v32, v38, v39
	v_cvt_pk_bf16_f32 v33, v36, v37
	v_cvt_pk_bf16_f32 v34, v34, v35
	v_cvt_pk_bf16_f32 v35, v40, v41
	v_lshl_add_u64 v[36:37], s[4:5], 0, v[82:83]
	global_store_dwordx4 v[36:37], v[32:35], off nt
	s_add_i32 s4, s33, 0x161000
	s_add_u32 s4, s20, s4
	s_nop 0
	v_cvt_f32_u32_e32 v32, v97
	v_cvt_f32_u32_e32 v33, v96
	s_addc_u32 s5, s68, 0
	s_add_i32 s33, s33, 0x161800
	v_fmac_f32_e32 v33, 0x4f800000, v32
	v_fmamk_f32 v32, v33, 0x30000000, v234
	v_rsq_f32_e32 v40, v32
	s_nop 0
	v_mul_f32_e32 v36, 0xbfb8aa3b, v40
	v_pk_mul_f32 v[34:35], v[30:31], v[36:37] op_sel_hi:[1,0]
	v_pk_mul_f32 v[32:33], v[28:29], v[36:37] op_sel_hi:[1,0]
	v_pk_mul_f32 v[38:39], v[22:23], v[36:37] op_sel_hi:[1,0]
	v_pk_mul_f32 v[36:37], v[20:21], v[36:37] op_sel_hi:[1,0]
	v_mul_f32_e32 v40, v40, v40
	v_pk_mul_f32 v[42:43], v[26:27], v[40:41] op_sel_hi:[1,0]
	v_exp_f32_e32 v32, v32
	v_exp_f32_e32 v36, v36
	v_exp_f32_e32 v33, v33
	v_exp_f32_e32 v37, v37
	v_exp_f32_e32 v34, v34
	v_exp_f32_e32 v38, v38
	v_exp_f32_e32 v35, v35
	v_exp_f32_e32 v39, v39
	v_pk_mul_f32 v[44:45], v[24:25], v[40:41] op_sel_hi:[1,0]
	v_pk_add_f32 v[24:25], v[32:33], 1.0 op_sel_hi:[1,0]
	v_pk_add_f32 v[26:27], v[34:35], 1.0 op_sel_hi:[1,0]
	v_pk_add_f32 v[30:31], v[38:39], 1.0 op_sel_hi:[1,0]
	v_pk_add_f32 v[28:29], v[36:37], 1.0 op_sel_hi:[1,0]
	v_pk_mul_f32 v[18:19], v[18:19], v[40:41] op_sel_hi:[1,0]
	v_pk_mul_f32 v[16:17], v[16:17], v[40:41] op_sel_hi:[1,0]
	v_rcp_f32_e32 v24, v24
	v_rcp_f32_e32 v28, v28
	v_rcp_f32_e32 v25, v25
	v_rcp_f32_e32 v29, v29
	v_rcp_f32_e32 v26, v26
	v_rcp_f32_e32 v30, v30
	v_rcp_f32_e32 v27, v27
	v_rcp_f32_e32 v31, v31
	s_nop 0
	v_pk_mul_f32 v[20:21], v[42:43], v[26:27]
	v_pk_mul_f32 v[22:23], v[44:45], v[24:25]
	v_pk_mul_f32 v[24:25], v[18:19], v[30:31]
	v_pk_mul_f32 v[18:19], v[16:17], v[28:29]
	v_cvt_pk_bf16_f32 v16, v22, v23
	v_cvt_pk_bf16_f32 v17, v20, v21
	v_cvt_pk_bf16_f32 v18, v18, v19
	v_cvt_pk_bf16_f32 v19, v24, v25
	v_lshl_add_u64 v[20:21], s[4:5], 0, v[82:83]
	global_store_dwordx4 v[20:21], v[16:19], off nt
	s_add_u32 s4, s20, s33
	s_addc_u32 s5, s68, 0
	s_nop 0
	v_cvt_f32_u32_e32 v16, v99
	v_cvt_f32_u32_e32 v17, v98
	s_andn2_b64 vcc, exec, s[38:39]
	v_fmac_f32_e32 v17, 0x4f800000, v16
	v_fmamk_f32 v16, v17, 0x30000000, v234
	v_rsq_f32_e32 v24, v16
	s_nop 0
	v_mul_f32_e32 v20, 0xbfb8aa3b, v24
	v_pk_mul_f32 v[18:19], v[14:15], v[20:21] op_sel_hi:[1,0]
	v_pk_mul_f32 v[16:17], v[12:13], v[20:21] op_sel_hi:[1,0]
	v_pk_mul_f32 v[22:23], v[6:7], v[20:21] op_sel_hi:[1,0]
	v_pk_mul_f32 v[20:21], v[4:5], v[20:21] op_sel_hi:[1,0]
	v_mul_f32_e32 v24, v24, v24
	v_pk_mul_f32 v[26:27], v[10:11], v[24:25] op_sel_hi:[1,0]
	v_exp_f32_e32 v16, v16
	v_exp_f32_e32 v20, v20
	v_exp_f32_e32 v17, v17
	v_exp_f32_e32 v21, v21
	v_exp_f32_e32 v18, v18
	v_exp_f32_e32 v22, v22
	v_exp_f32_e32 v19, v19
	v_exp_f32_e32 v23, v23
	v_pk_mul_f32 v[28:29], v[8:9], v[24:25] op_sel_hi:[1,0]
	v_pk_add_f32 v[8:9], v[16:17], 1.0 op_sel_hi:[1,0]
	v_pk_add_f32 v[10:11], v[18:19], 1.0 op_sel_hi:[1,0]
	v_pk_add_f32 v[14:15], v[22:23], 1.0 op_sel_hi:[1,0]
	v_pk_add_f32 v[12:13], v[20:21], 1.0 op_sel_hi:[1,0]
	v_pk_mul_f32 v[2:3], v[2:3], v[24:25] op_sel_hi:[1,0]
	v_pk_mul_f32 v[0:1], v[0:1], v[24:25] op_sel_hi:[1,0]
	v_rcp_f32_e32 v8, v8
	v_rcp_f32_e32 v12, v12
	v_rcp_f32_e32 v9, v9
	v_rcp_f32_e32 v13, v13
	v_rcp_f32_e32 v10, v10
	v_rcp_f32_e32 v14, v14
	v_rcp_f32_e32 v11, v11
	v_rcp_f32_e32 v15, v15
	s_nop 0
	v_pk_mul_f32 v[4:5], v[26:27], v[10:11]
	v_pk_mul_f32 v[6:7], v[28:29], v[8:9]
	v_pk_mul_f32 v[8:9], v[2:3], v[14:15]
	v_pk_mul_f32 v[2:3], v[0:1], v[12:13]
	v_cvt_pk_bf16_f32 v0, v6, v7
	v_cvt_pk_bf16_f32 v1, v4, v5
	v_cvt_pk_bf16_f32 v2, v2, v3
	v_cvt_pk_bf16_f32 v3, v8, v9
	v_lshl_add_u64 v[4:5], s[4:5], 0, v[82:83]
	s_mov_b64 s[4:5], -1
	global_store_dwordx4 v[4:5], v[0:3], off nt
	s_cbranch_vccnz .LBB0_791
	s_andn2_b64 vcc, exec, s[0:1]
	s_cbranch_vccnz .LBB0_790
	s_barrier
	s_branch .LBB0_790

.Lpeel_p6:
	s_waitcnt lgkmcnt(0)
	s_add_i32 s11, s8, 0xffea4000
	s_cmpk_eq_i32 s10, 0x54
	s_cselect_b32 s13, s6, s11
	s_cselect_b32 s12, s7, s9
	s_or_b32 s11, s13, 0x4000
	s_mov_b32 m0, s87
	s_nop 0
	buffer_load_dwordx4 v220, s[20:23], s8 offen lds
	s_nop 0
	s_mov_b32 m0, s89
	s_nop 0
	buffer_load_dwordx4 v221, s[20:23], s8 offen lds
	s_waitcnt vmcnt(24) lgkmcnt(0)
	s_barrier
	s_waitcnt lgkmcnt(7)
	v_mfma_f32_16x16x32_bf16 v[164:167], v[128:131], v[184:187], 0
	v_mfma_f32_16x16x32_bf16 v[160:163], v[152:155], v[184:187], 0
	s_waitcnt lgkmcnt(5)
	v_mfma_f32_16x16x32_bf16 v[136:139], v[128:131], v[192:195], 0
	v_mfma_f32_16x16x32_bf16 v[132:135], v[152:155], v[192:195], 0
	s_waitcnt lgkmcnt(3)
	v_mfma_f32_16x16x32_bf16 v[116:119], v[128:131], v[200:203], 0
	v_mfma_f32_16x16x32_bf16 v[112:115], v[152:155], v[200:203], 0
	s_waitcnt lgkmcnt(1)
	v_mfma_f32_16x16x32_bf16 v[76:79], v[128:131], v[224:227], 0
	v_mfma_f32_16x16x32_bf16 v[72:75], v[152:155], v[224:227], 0
	v_mfma_f32_16x16x32_bf16 v[164:167], v[140:143], v[188:191], v[164:167]
	v_mfma_f32_16x16x32_bf16 v[160:163], v[156:159], v[188:191], v[160:163]
	v_mfma_f32_16x16x32_bf16 v[136:139], v[140:143], v[196:199], v[136:139]
	v_mfma_f32_16x16x32_bf16 v[132:135], v[156:159], v[196:199], v[132:135]
	v_mfma_f32_16x16x32_bf16 v[116:119], v[140:143], v[204:207], v[116:119]
	v_mfma_f32_16x16x32_bf16 v[112:115], v[156:159], v[204:207], v[112:115]
	s_waitcnt lgkmcnt(0)
	v_mfma_f32_16x16x32_bf16 v[76:79], v[140:143], v[228:231], v[76:79]
	v_mfma_f32_16x16x32_bf16 v[72:75], v[156:159], v[228:231], v[72:75]
	v_mfma_f32_16x16x32_bf16 v[148:151], v[168:171], v[184:187], 0
	v_mfma_f32_16x16x32_bf16 v[144:147], v[176:179], v[184:187], 0
	v_mfma_f32_16x16x32_bf16 v[124:127], v[168:171], v[192:195], 0
	v_mfma_f32_16x16x32_bf16 v[120:123], v[176:179], v[192:195], 0
	v_mfma_f32_16x16x32_bf16 v[108:111], v[168:171], v[200:203], 0
	v_mfma_f32_16x16x32_bf16 v[104:107], v[176:179], v[200:203], 0
	v_mfma_f32_16x16x32_bf16 v[68:71], v[168:171], v[224:227], 0
	v_mfma_f32_16x16x32_bf16 v[64:67], v[176:179], v[224:227], 0
	v_mfma_f32_16x16x32_bf16 v[148:151], v[172:175], v[188:191], v[148:151]
	v_mfma_f32_16x16x32_bf16 v[144:147], v[180:183], v[188:191], v[144:147]
	v_mfma_f32_16x16x32_bf16 v[124:127], v[172:175], v[196:199], v[124:127]
	v_mfma_f32_16x16x32_bf16 v[120:123], v[180:183], v[196:199], v[120:123]
	v_mfma_f32_16x16x32_bf16 v[108:111], v[172:175], v[204:207], v[108:111]
	v_mfma_f32_16x16x32_bf16 v[104:107], v[180:183], v[204:207], v[104:107]
	v_mfma_f32_16x16x32_bf16 v[68:71], v[172:175], v[228:231], v[68:71]
	v_mfma_f32_16x16x32_bf16 v[64:67], v[180:183], v[228:231], v[64:67]
	s_barrier
	ds_read_b128 v[184:187], v223 offset:16384
	ds_read_b128 v[188:191], v223 offset:17408
	ds_read_b128 v[192:195], v223 offset:18432
	ds_read_b128 v[196:199], v223 offset:19456
	ds_read_b128 v[200:203], v223 offset:20480
	ds_read_b128 v[204:207], v223 offset:21504
	ds_read_b128 v[224:227], v223 offset:22528
	ds_read_b128 v[228:231], v223 offset:23552
	s_mov_b32 m0, s51
	s_nop 0
	buffer_load_dwordx4 v220, s[52:55], s12 offen lds
	s_add_i32 s14, s12, 0x160000
	s_mov_b32 m0, s74
	s_nop 0
	buffer_load_dwordx4 v221, s[52:55], s12 offen lds
	s_nop 0
	s_mov_b32 m0, s75
	s_nop 0
	buffer_load_dwordx4 v220, s[52:55], s14 offen lds
	s_nop 0
	s_mov_b32 m0, s76
	s_nop 0
	buffer_load_dwordx4 v221, s[52:55], s14 offen lds
	s_nop 0
	s_mov_b32 m0, s31
	s_nop 0
	buffer_load_dwordx4 v220, s[20:23], s13 offen lds
	s_nop 0
	s_mov_b32 m0, s77
	s_nop 0
	buffer_load_dwordx4 v221, s[20:23], s13 offen lds
	s_waitcnt vmcnt(24) lgkmcnt(0)
	s_barrier
	s_waitcnt lgkmcnt(7)
	v_mfma_f32_16x16x32_bf16 v[60:63], v[128:131], v[184:187], 0
	v_mfma_f32_16x16x32_bf16 v[56:59], v[152:155], v[184:187], 0
	s_waitcnt lgkmcnt(5)
	v_mfma_f32_16x16x32_bf16 v[44:47], v[128:131], v[192:195], 0
	v_mfma_f32_16x16x32_bf16 v[40:43], v[152:155], v[192:195], 0
	s_waitcnt lgkmcnt(3)
	v_mfma_f32_16x16x32_bf16 v[28:31], v[128:131], v[200:203], 0
	v_mfma_f32_16x16x32_bf16 v[24:27], v[152:155], v[200:203], 0
	s_waitcnt lgkmcnt(1)
	v_mfma_f32_16x16x32_bf16 v[12:15], v[128:131], v[224:227], 0
	v_mfma_f32_16x16x32_bf16 v[8:11], v[152:155], v[224:227], 0
	v_mfma_f32_16x16x32_bf16 v[60:63], v[140:143], v[188:191], v[60:63]
	v_mfma_f32_16x16x32_bf16 v[56:59], v[156:159], v[188:191], v[56:59]
	v_mfma_f32_16x16x32_bf16 v[44:47], v[140:143], v[196:199], v[44:47]
	v_mfma_f32_16x16x32_bf16 v[40:43], v[156:159], v[196:199], v[40:43]
	v_mfma_f32_16x16x32_bf16 v[28:31], v[140:143], v[204:207], v[28:31]
	v_mfma_f32_16x16x32_bf16 v[24:27], v[156:159], v[204:207], v[24:27]
	s_waitcnt lgkmcnt(0)
	v_mfma_f32_16x16x32_bf16 v[12:15], v[140:143], v[228:231], v[12:15]
	v_mfma_f32_16x16x32_bf16 v[8:11], v[156:159], v[228:231], v[8:11]
	v_mfma_f32_16x16x32_bf16 v[52:55], v[168:171], v[184:187], 0
	v_mfma_f32_16x16x32_bf16 v[48:51], v[176:179], v[184:187], 0
	v_mfma_f32_16x16x32_bf16 v[36:39], v[168:171], v[192:195], 0
	v_mfma_f32_16x16x32_bf16 v[32:35], v[176:179], v[192:195], 0
	v_mfma_f32_16x16x32_bf16 v[20:23], v[168:171], v[200:203], 0
	v_mfma_f32_16x16x32_bf16 v[16:19], v[176:179], v[200:203], 0
	v_mfma_f32_16x16x32_bf16 v[4:7], v[168:171], v[224:227], 0
	v_mfma_f32_16x16x32_bf16 v[0:3], v[176:179], v[224:227], 0
	v_mfma_f32_16x16x32_bf16 v[52:55], v[172:175], v[188:191], v[52:55]
	v_mfma_f32_16x16x32_bf16 v[48:51], v[180:183], v[188:191], v[48:51]
	v_mfma_f32_16x16x32_bf16 v[36:39], v[172:175], v[196:199], v[36:39]
	v_mfma_f32_16x16x32_bf16 v[32:35], v[180:183], v[196:199], v[32:35]
	v_mfma_f32_16x16x32_bf16 v[20:23], v[172:175], v[204:207], v[20:23]
	v_mfma_f32_16x16x32_bf16 v[16:19], v[180:183], v[204:207], v[16:19]
	v_mfma_f32_16x16x32_bf16 v[4:7], v[172:175], v[228:231], v[4:7]
	v_mfma_f32_16x16x32_bf16 v[0:3], v[180:183], v[228:231], v[0:3]
	s_barrier
	v_add_u32_e32 v156, 0x18000, v222
	v_add_u32_e32 v180, 0x1c000, v222
	ds_read_b128 v[128:131], v156
	ds_read_b128 v[140:143], v156 offset:1024
	ds_read_b128 v[152:155], v156 offset:2048
	ds_read_b128 v[156:159], v156 offset:3072
	ds_read_b128 v[168:171], v180
	ds_read_b128 v[172:175], v180 offset:1024
	ds_read_b128 v[176:179], v180 offset:2048
	ds_read_b128 v[180:183], v180 offset:3072
	ds_read_b128 v[184:187], v223 offset:32768
	ds_read_b128 v[188:191], v223 offset:33792
	ds_read_b128 v[192:195], v223 offset:34816
	ds_read_b128 v[196:199], v223 offset:35840
	ds_read_b128 v[200:203], v223 offset:36864
	ds_read_b128 v[204:207], v223 offset:37888
	ds_read_b128 v[224:227], v223 offset:38912
	ds_read_b128 v[228:231], v223 offset:39936
	s_add_i32 s13, s13, 0x160000
	s_mov_b32 m0, s78
	s_nop 0
	buffer_load_dwordx4 v220, s[20:23], s13 offen lds
	s_nop 0
	s_mov_b32 m0, s79
	s_nop 0
	buffer_load_dwordx4 v221, s[20:23], s13 offen lds
	s_waitcnt vmcnt(8) lgkmcnt(0)
	s_barrier
	s_waitcnt lgkmcnt(7)
	v_mfma_f32_16x16x32_bf16 v[164:167], v[128:131], v[184:187], v[164:167]
	v_mfma_f32_16x16x32_bf16 v[160:163], v[152:155], v[184:187], v[160:163]
	s_waitcnt lgkmcnt(5)
	v_mfma_f32_16x16x32_bf16 v[136:139], v[128:131], v[192:195], v[136:139]
	v_mfma_f32_16x16x32_bf16 v[132:135], v[152:155], v[192:195], v[132:135]
	s_waitcnt lgkmcnt(3)
	v_mfma_f32_16x16x32_bf16 v[116:119], v[128:131], v[200:203], v[116:119]
	v_mfma_f32_16x16x32_bf16 v[112:115], v[152:155], v[200:203], v[112:115]
	s_waitcnt lgkmcnt(1)
	v_mfma_f32_16x16x32_bf16 v[76:79], v[128:131], v[224:227], v[76:79]
	v_mfma_f32_16x16x32_bf16 v[72:75], v[152:155], v[224:227], v[72:75]
	v_mfma_f32_16x16x32_bf16 v[164:167], v[140:143], v[188:191], v[164:167]
	v_mfma_f32_16x16x32_bf16 v[160:163], v[156:159], v[188:191], v[160:163]
	v_mfma_f32_16x16x32_bf16 v[136:139], v[140:143], v[196:199], v[136:139]
	v_mfma_f32_16x16x32_bf16 v[132:135], v[156:159], v[196:199], v[132:135]
	v_mfma_f32_16x16x32_bf16 v[116:119], v[140:143], v[204:207], v[116:119]
	v_mfma_f32_16x16x32_bf16 v[112:115], v[156:159], v[204:207], v[112:115]
	s_waitcnt lgkmcnt(0)
	v_mfma_f32_16x16x32_bf16 v[76:79], v[140:143], v[228:231], v[76:79]
	v_mfma_f32_16x16x32_bf16 v[72:75], v[156:159], v[228:231], v[72:75]
	v_mfma_f32_16x16x32_bf16 v[148:151], v[168:171], v[184:187], v[148:151]
	v_mfma_f32_16x16x32_bf16 v[144:147], v[176:179], v[184:187], v[144:147]
	v_mfma_f32_16x16x32_bf16 v[124:127], v[168:171], v[192:195], v[124:127]
	v_mfma_f32_16x16x32_bf16 v[120:123], v[176:179], v[192:195], v[120:123]
	v_mfma_f32_16x16x32_bf16 v[108:111], v[168:171], v[200:203], v[108:111]
	v_mfma_f32_16x16x32_bf16 v[104:107], v[176:179], v[200:203], v[104:107]
	v_mfma_f32_16x16x32_bf16 v[68:71], v[168:171], v[224:227], v[68:71]
	v_mfma_f32_16x16x32_bf16 v[64:67], v[176:179], v[224:227], v[64:67]
	v_mfma_f32_16x16x32_bf16 v[148:151], v[172:175], v[188:191], v[148:151]
	v_mfma_f32_16x16x32_bf16 v[144:147], v[180:183], v[188:191], v[144:147]
	v_mfma_f32_16x16x32_bf16 v[124:127], v[172:175], v[196:199], v[124:127]
	v_mfma_f32_16x16x32_bf16 v[120:123], v[180:183], v[196:199], v[120:123]
	v_mfma_f32_16x16x32_bf16 v[108:111], v[172:175], v[204:207], v[108:111]
	v_mfma_f32_16x16x32_bf16 v[104:107], v[180:183], v[204:207], v[104:107]
	v_mfma_f32_16x16x32_bf16 v[68:71], v[172:175], v[228:231], v[68:71]
	v_mfma_f32_16x16x32_bf16 v[64:67], v[180:183], v[228:231], v[64:67]
	s_barrier
	ds_read_b128 v[184:187], v223 offset:49152
	ds_read_b128 v[188:191], v223 offset:50176
	ds_read_b128 v[192:195], v223 offset:51200
	ds_read_b128 v[196:199], v223 offset:52224
	ds_read_b128 v[200:203], v223 offset:53248
	ds_read_b128 v[204:207], v223 offset:54272
	ds_read_b128 v[224:227], v223 offset:55296
	ds_read_b128 v[228:231], v223 offset:56320
	s_or_b32 s13, s12, 0x4000
	s_mov_b32 m0, s34
	s_nop 0
	buffer_load_dwordx4 v220, s[52:55], s13 offen lds
	s_add_i32 s12, s12, 0x164000
	s_mov_b32 m0, s82
	s_nop 0
	buffer_load_dwordx4 v221, s[52:55], s13 offen lds
	s_nop 0
	s_mov_b32 m0, s85
	s_nop 0
	buffer_load_dwordx4 v220, s[52:55], s12 offen lds
	s_nop 0
	s_mov_b32 m0, s86
	s_nop 0
	buffer_load_dwordx4 v221, s[52:55], s12 offen lds
	s_nop 0
	s_mov_b32 m0, s83
	s_nop 0
	buffer_load_dwordx4 v220, s[20:23], s11 offen lds
	s_nop 0
	s_mov_b32 m0, s84
	s_nop 0
	buffer_load_dwordx4 v221, s[20:23], s11 offen lds
	s_waitcnt vmcnt(8) lgkmcnt(0)
	s_barrier
	s_waitcnt lgkmcnt(7)
	v_mfma_f32_16x16x32_bf16 v[60:63], v[128:131], v[184:187], v[60:63]
	v_mfma_f32_16x16x32_bf16 v[56:59], v[152:155], v[184:187], v[56:59]
	s_waitcnt lgkmcnt(5)
	v_mfma_f32_16x16x32_bf16 v[44:47], v[128:131], v[192:195], v[44:47]
	v_mfma_f32_16x16x32_bf16 v[40:43], v[152:155], v[192:195], v[40:43]
	s_waitcnt lgkmcnt(3)
	v_mfma_f32_16x16x32_bf16 v[28:31], v[128:131], v[200:203], v[28:31]
	v_mfma_f32_16x16x32_bf16 v[24:27], v[152:155], v[200:203], v[24:27]
	s_waitcnt lgkmcnt(1)
	v_mfma_f32_16x16x32_bf16 v[12:15], v[128:131], v[224:227], v[12:15]
	v_mfma_f32_16x16x32_bf16 v[8:11], v[152:155], v[224:227], v[8:11]
	v_mfma_f32_16x16x32_bf16 v[60:63], v[140:143], v[188:191], v[60:63]
	v_mfma_f32_16x16x32_bf16 v[56:59], v[156:159], v[188:191], v[56:59]
	v_mfma_f32_16x16x32_bf16 v[44:47], v[140:143], v[196:199], v[44:47]
	v_mfma_f32_16x16x32_bf16 v[40:43], v[156:159], v[196:199], v[40:43]
	v_mfma_f32_16x16x32_bf16 v[28:31], v[140:143], v[204:207], v[28:31]
	v_mfma_f32_16x16x32_bf16 v[24:27], v[156:159], v[204:207], v[24:27]
	s_waitcnt lgkmcnt(0)
	v_mfma_f32_16x16x32_bf16 v[12:15], v[140:143], v[228:231], v[12:15]
	v_mfma_f32_16x16x32_bf16 v[8:11], v[156:159], v[228:231], v[8:11]
	v_mfma_f32_16x16x32_bf16 v[52:55], v[168:171], v[184:187], v[52:55]
	v_mfma_f32_16x16x32_bf16 v[48:51], v[176:179], v[184:187], v[48:51]
	v_mfma_f32_16x16x32_bf16 v[36:39], v[168:171], v[192:195], v[36:39]
	v_mfma_f32_16x16x32_bf16 v[32:35], v[176:179], v[192:195], v[32:35]
	v_mfma_f32_16x16x32_bf16 v[20:23], v[168:171], v[200:203], v[20:23]
	v_mfma_f32_16x16x32_bf16 v[16:19], v[176:179], v[200:203], v[16:19]
	v_mfma_f32_16x16x32_bf16 v[4:7], v[168:171], v[224:227], v[4:7]
	v_mfma_f32_16x16x32_bf16 v[0:3], v[176:179], v[224:227], v[0:3]
	v_mfma_f32_16x16x32_bf16 v[52:55], v[172:175], v[188:191], v[52:55]
	v_mfma_f32_16x16x32_bf16 v[48:51], v[180:183], v[188:191], v[48:51]
	v_mfma_f32_16x16x32_bf16 v[36:39], v[172:175], v[196:199], v[36:39]
	v_mfma_f32_16x16x32_bf16 v[32:35], v[180:183], v[196:199], v[32:35]
	v_mfma_f32_16x16x32_bf16 v[20:23], v[172:175], v[204:207], v[20:23]
	v_mfma_f32_16x16x32_bf16 v[16:19], v[180:183], v[204:207], v[16:19]
	v_mfma_f32_16x16x32_bf16 v[4:7], v[172:175], v[228:231], v[4:7]
	v_mfma_f32_16x16x32_bf16 v[0:3], v[180:183], v[228:231], v[0:3]
	s_barrier
	s_add_i32 s10, s10, 2
	s_add_i32 s8, s8, 0x8000
	s_add_i32 s9, s9, 0x8000
